# v42 + first K-iteration peeled: first MFMA of every accumulator takes C=0, the 128 per-tile zeroing v_movs are deleted
# speedup vs baseline: 1.0281x; 1.0027x over previous
.LBB0_260:
	s_ashr_i32 s65, s64, 31
	s_lshl_b64 s[22:23], s[64:65], 20
	s_add_u32 s62, s79, s22
	s_addc_u32 s63, s28, s23
	s_and_b64 s[22:23], s[4:5], exec
	s_cselect_b32 s22, s63, s77
	s_cselect_b32 s23, s62, s76
	s_ashr_i32 s49, s48, 31
	s_lshl_b64 s[70:71], s[48:49], 20
	s_add_u32 s70, s8, s70
	s_addc_u32 s71, s9, s71
	s_and_b64 s[90:91], s[4:5], exec
	s_cselect_b32 s49, s71, s85
	s_cselect_b32 s57, s70, s84
	s_ashr_i32 s51, s50, 31
	s_lshl_b32 s90, s44, 8
	s_lshl_b64 vcc, s[50:51], 10
	s_ashr_i32 s0, s50, 5
	s_ashr_i32 s91, s90, 31
	s_add_u32 s76, s76, 0x80080
	v_lshl_add_u64 v[2:3], s[90:91], 2, v[134:135]
	v_mov_b32_e32 v4, 0x6000
	s_addc_u32 s77, s77, 0
	v_lshl_add_u64 v[142:143], v[136:137], 0, vcc
	v_mad_i64_i32 v[144:145], vcc, s0, v4, v[2:3]
	s_add_u32 s51, s84, 0x100
	s_addc_u32 s58, s85, 0
	s_mov_b32 s65, -2
	s_branch .LBB0_262

.Lpeel_disp_ine:
	s_cmp_lg_u32 s65, -2
	s_cbranch_scc1 .LBB0_261
	s_add_u32 s0, s76, 0xfff80080
	s_addc_u32 s1, s77, -1
	s_and_b64 s[84:85], s[84:85], exec
	s_cselect_b32 vcc_hi, s22, s1
	s_cselect_b32 vcc_lo, s23, s0
	s_cselect_b32 s85, s49, s58
	s_cselect_b32 s84, s57, s51
	s_add_i32 s0, 0, 0x10000
	s_add_i32 s1, 0, 0x14000
	v_add_u32_e32 v158, s0, v176
	v_add_u32_e32 v174, s1, v176
	ds_read_b128 v[146:149], v158
	ds_read_b128 v[150:153], v158 offset:1024
	ds_read_b128 v[154:157], v158 offset:2048
	ds_read_b128 v[158:161], v158 offset:3072
	ds_read_b128 v[162:165], v174
	ds_read_b128 v[166:169], v174 offset:1024
	ds_read_b128 v[170:173], v174 offset:2048
	ds_read_b128 v[178:181], v174 offset:3072
	s_add_i32 m0, s21, 0xc000
	ds_read_b128 v[182:185], v177
	ds_read_b128 v[186:189], v177 offset:1024
	ds_read_b128 v[190:193], v177 offset:2048
	ds_read_b128 v[204:207], v177 offset:3072
	ds_read_b128 v[208:211], v177 offset:4096
	ds_read_b128 v[212:215], v177 offset:5120
	ds_read_b128 v[216:219], v177 offset:6144
	ds_read_b128 v[220:223], v177 offset:7168
	global_load_lds_dwordx4 v138, s[76:77]
	s_add_i32 m0, s21, 0xe000
	s_nop 0
	global_load_lds_dwordx4 v140, s[76:77]
	s_waitcnt vmcnt(8)
	s_waitcnt lgkmcnt(0)
	s_barrier
	s_setprio 1
	s_waitcnt lgkmcnt(0)
	v_mfma_f32_16x16x32_bf16 v[126:129], v[146:149], v[182:185], 0
	v_mfma_f32_16x16x32_bf16 v[126:129], v[150:153], v[186:189], v[126:129]
	v_mfma_f32_16x16x32_bf16 v[122:125], v[158:161], v[186:189], 0
	v_mfma_f32_16x16x32_bf16 v[122:125], v[154:157], v[182:185], v[122:125]
	v_mfma_f32_16x16x32_bf16 v[118:121], v[162:165], v[182:185], 0
	v_mfma_f32_16x16x32_bf16 v[118:121], v[166:169], v[186:189], v[118:121]
	v_mfma_f32_16x16x32_bf16 v[114:117], v[178:181], v[186:189], 0
	v_mfma_f32_16x16x32_bf16 v[114:117], v[170:173], v[182:185], v[114:117]
	v_mfma_f32_16x16x32_bf16 v[98:101], v[170:173], v[190:193], 0
	v_mfma_f32_16x16x32_bf16 v[98:101], v[178:181], v[204:207], v[98:101]
	v_mfma_f32_16x16x32_bf16 v[102:105], v[166:169], v[204:207], 0
	v_mfma_f32_16x16x32_bf16 v[102:105], v[162:165], v[190:193], v[102:105]
	v_mfma_f32_16x16x32_bf16 v[106:109], v[154:157], v[190:193], 0
	v_mfma_f32_16x16x32_bf16 v[106:109], v[158:161], v[204:207], v[106:109]
	v_mfma_f32_16x16x32_bf16 v[110:113], v[150:153], v[204:207], 0
	v_mfma_f32_16x16x32_bf16 v[110:113], v[146:149], v[190:193], v[110:113]
	v_mfma_f32_16x16x32_bf16 v[94:97], v[146:149], v[208:211], 0
	v_mfma_f32_16x16x32_bf16 v[94:97], v[150:153], v[212:215], v[94:97]
	v_mfma_f32_16x16x32_bf16 v[90:93], v[158:161], v[212:215], 0
	v_mfma_f32_16x16x32_bf16 v[90:93], v[154:157], v[208:211], v[90:93]
	v_mfma_f32_16x16x32_bf16 v[86:89], v[162:165], v[208:211], 0
	v_mfma_f32_16x16x32_bf16 v[86:89], v[166:169], v[212:215], v[86:89]
	v_mfma_f32_16x16x32_bf16 v[82:85], v[178:181], v[212:215], 0
	v_mfma_f32_16x16x32_bf16 v[82:85], v[170:173], v[208:211], v[82:85]
	v_mfma_f32_16x16x32_bf16 v[66:69], v[170:173], v[216:219], 0
	v_mfma_f32_16x16x32_bf16 v[66:69], v[178:181], v[220:223], v[66:69]
	v_mfma_f32_16x16x32_bf16 v[70:73], v[166:169], v[220:223], 0
	v_mfma_f32_16x16x32_bf16 v[70:73], v[162:165], v[216:219], v[70:73]
	v_mfma_f32_16x16x32_bf16 v[74:77], v[154:157], v[216:219], 0
	v_mfma_f32_16x16x32_bf16 v[74:77], v[158:161], v[220:223], v[74:77]
	v_mfma_f32_16x16x32_bf16 v[78:81], v[150:153], v[220:223], 0
	v_mfma_f32_16x16x32_bf16 v[78:81], v[146:149], v[216:219], v[78:81]
	s_setprio 0
	s_barrier
	s_add_i32 s0, s0, s20
	s_mov_b32 m0, s0
	ds_read_b128 v[182:185], v177 offset:16384
	ds_read_b128 v[186:189], v177 offset:17408
	ds_read_b128 v[190:193], v177 offset:18432
	ds_read_b128 v[204:207], v177 offset:19456
	ds_read_b128 v[208:211], v177 offset:20480
	ds_read_b128 v[212:215], v177 offset:21504
	ds_read_b128 v[216:219], v177 offset:22528
	ds_read_b128 v[220:223], v177 offset:23552
	global_load_lds_dwordx4 v132, s[84:85]
	s_add_i32 m0, s0, 0x2000
	s_add_u32 s94, s84, 0x80000
	s_addc_u32 s95, s85, 0
	s_add_i32 s0, s1, s20
	global_load_lds_dwordx4 v130, s[84:85]
	s_mov_b32 m0, s0
	s_nop 0
	global_load_lds_dwordx4 v132, s[94:95]
	s_add_i32 m0, s0, 0x2000
	s_nop 0
	global_load_lds_dwordx4 v130, s[94:95]
	s_mov_b32 m0, s21
	s_nop 0
	global_load_lds_dwordx4 v132, vcc
	s_mov_b32 m0, s26
	s_nop 0
	global_load_lds_dwordx4 v130, vcc
	s_waitcnt vmcnt(8)
	s_waitcnt lgkmcnt(0)
	s_barrier
	s_setprio 1
	s_waitcnt lgkmcnt(0)
	v_mfma_f32_16x16x32_bf16 v[62:65], v[146:149], v[182:185], 0
	v_mfma_f32_16x16x32_bf16 v[62:65], v[150:153], v[186:189], v[62:65]
	v_mfma_f32_16x16x32_bf16 v[58:61], v[158:161], v[186:189], 0
	v_mfma_f32_16x16x32_bf16 v[58:61], v[154:157], v[182:185], v[58:61]
	v_mfma_f32_16x16x32_bf16 v[54:57], v[162:165], v[182:185], 0
	v_mfma_f32_16x16x32_bf16 v[54:57], v[166:169], v[186:189], v[54:57]
	v_mfma_f32_16x16x32_bf16 v[50:53], v[178:181], v[186:189], 0
	v_mfma_f32_16x16x32_bf16 v[50:53], v[170:173], v[182:185], v[50:53]
	v_mfma_f32_16x16x32_bf16 v[34:37], v[170:173], v[190:193], 0
	v_mfma_f32_16x16x32_bf16 v[34:37], v[178:181], v[204:207], v[34:37]
	v_mfma_f32_16x16x32_bf16 v[38:41], v[166:169], v[204:207], 0
	v_mfma_f32_16x16x32_bf16 v[38:41], v[162:165], v[190:193], v[38:41]
	v_mfma_f32_16x16x32_bf16 v[42:45], v[154:157], v[190:193], 0
	v_mfma_f32_16x16x32_bf16 v[42:45], v[158:161], v[204:207], v[42:45]
	v_mfma_f32_16x16x32_bf16 v[46:49], v[150:153], v[204:207], 0
	v_mfma_f32_16x16x32_bf16 v[46:49], v[146:149], v[190:193], v[46:49]
	v_mfma_f32_16x16x32_bf16 v[30:33], v[146:149], v[208:211], 0
	v_mfma_f32_16x16x32_bf16 v[30:33], v[150:153], v[212:215], v[30:33]
	v_mfma_f32_16x16x32_bf16 v[26:29], v[158:161], v[212:215], 0
	v_mfma_f32_16x16x32_bf16 v[26:29], v[154:157], v[208:211], v[26:29]
	v_mfma_f32_16x16x32_bf16 v[22:25], v[162:165], v[208:211], 0
	v_mfma_f32_16x16x32_bf16 v[22:25], v[166:169], v[212:215], v[22:25]
	v_mfma_f32_16x16x32_bf16 v[18:21], v[178:181], v[212:215], 0
	v_mfma_f32_16x16x32_bf16 v[18:21], v[170:173], v[208:211], v[18:21]
	v_mfma_f32_16x16x32_bf16 v[2:5], v[170:173], v[216:219], 0
	v_mfma_f32_16x16x32_bf16 v[2:5], v[178:181], v[220:223], v[2:5]
	v_mfma_f32_16x16x32_bf16 v[6:9], v[166:169], v[220:223], 0
	v_mfma_f32_16x16x32_bf16 v[6:9], v[162:165], v[216:219], v[6:9]
	v_mfma_f32_16x16x32_bf16 v[10:13], v[154:157], v[216:219], 0
	v_mfma_f32_16x16x32_bf16 v[10:13], v[158:161], v[220:223], v[10:13]
	v_mfma_f32_16x16x32_bf16 v[14:17], v[150:153], v[220:223], 0
	v_mfma_f32_16x16x32_bf16 v[14:17], v[146:149], v[216:219], v[14:17]
	s_setprio 0
	s_barrier
	s_add_i32 s0, 0, 0x18000
	s_add_i32 s1, 0, 0x1c000
	v_add_u32_e32 v158, s0, v176
	v_add_u32_e32 v178, s1, v176
	ds_read_b128 v[146:149], v158
	ds_read_b128 v[150:153], v158 offset:1024
	ds_read_b128 v[154:157], v158 offset:2048
	ds_read_b128 v[158:161], v158 offset:3072
	ds_read_b128 v[162:165], v178
	ds_read_b128 v[166:169], v178 offset:1024
	ds_read_b128 v[170:173], v178 offset:2048
	ds_read_b128 v[178:181], v178 offset:3072
	s_add_u32 s94, vcc_lo, 0x80000
	s_addc_u32 s95, vcc_hi, 0
	s_mov_b32 m0, s27
	ds_read_b128 v[182:185], v177 offset:32768
	ds_read_b128 v[186:189], v177 offset:33792
	ds_read_b128 v[190:193], v177 offset:34816
	ds_read_b128 v[204:207], v177 offset:35840
	ds_read_b128 v[208:211], v177 offset:36864
	ds_read_b128 v[212:215], v177 offset:37888
	ds_read_b128 v[216:219], v177 offset:38912
	ds_read_b128 v[220:223], v177 offset:39936
	global_load_lds_dwordx4 v132, s[94:95]
	s_mov_b32 m0, s29
	s_nop 0
	global_load_lds_dwordx4 v130, s[94:95]
	s_waitcnt vmcnt(8)
	s_waitcnt lgkmcnt(0)
	s_barrier
	s_setprio 1
	s_waitcnt lgkmcnt(0)
	v_mfma_f32_16x16x32_bf16 v[126:129], v[146:149], v[182:185], v[126:129]
	v_mfma_f32_16x16x32_bf16 v[126:129], v[150:153], v[186:189], v[126:129]
	v_mfma_f32_16x16x32_bf16 v[122:125], v[158:161], v[186:189], v[122:125]
	v_mfma_f32_16x16x32_bf16 v[122:125], v[154:157], v[182:185], v[122:125]
	v_mfma_f32_16x16x32_bf16 v[118:121], v[162:165], v[182:185], v[118:121]
	v_mfma_f32_16x16x32_bf16 v[118:121], v[166:169], v[186:189], v[118:121]
	v_mfma_f32_16x16x32_bf16 v[114:117], v[178:181], v[186:189], v[114:117]
	v_mfma_f32_16x16x32_bf16 v[114:117], v[170:173], v[182:185], v[114:117]
	v_mfma_f32_16x16x32_bf16 v[98:101], v[170:173], v[190:193], v[98:101]
	v_mfma_f32_16x16x32_bf16 v[98:101], v[178:181], v[204:207], v[98:101]
	v_mfma_f32_16x16x32_bf16 v[102:105], v[166:169], v[204:207], v[102:105]
	v_mfma_f32_16x16x32_bf16 v[102:105], v[162:165], v[190:193], v[102:105]
	v_mfma_f32_16x16x32_bf16 v[106:109], v[154:157], v[190:193], v[106:109]
	v_mfma_f32_16x16x32_bf16 v[106:109], v[158:161], v[204:207], v[106:109]
	v_mfma_f32_16x16x32_bf16 v[110:113], v[150:153], v[204:207], v[110:113]
	v_mfma_f32_16x16x32_bf16 v[110:113], v[146:149], v[190:193], v[110:113]
	v_mfma_f32_16x16x32_bf16 v[94:97], v[146:149], v[208:211], v[94:97]
	v_mfma_f32_16x16x32_bf16 v[94:97], v[150:153], v[212:215], v[94:97]
	v_mfma_f32_16x16x32_bf16 v[90:93], v[158:161], v[212:215], v[90:93]
	v_mfma_f32_16x16x32_bf16 v[90:93], v[154:157], v[208:211], v[90:93]
	v_mfma_f32_16x16x32_bf16 v[86:89], v[162:165], v[208:211], v[86:89]
	v_mfma_f32_16x16x32_bf16 v[86:89], v[166:169], v[212:215], v[86:89]
	v_mfma_f32_16x16x32_bf16 v[82:85], v[178:181], v[212:215], v[82:85]
	v_mfma_f32_16x16x32_bf16 v[82:85], v[170:173], v[208:211], v[82:85]
	v_mfma_f32_16x16x32_bf16 v[66:69], v[170:173], v[216:219], v[66:69]
	v_mfma_f32_16x16x32_bf16 v[66:69], v[178:181], v[220:223], v[66:69]
	v_mfma_f32_16x16x32_bf16 v[70:73], v[166:169], v[220:223], v[70:73]
	v_mfma_f32_16x16x32_bf16 v[70:73], v[162:165], v[216:219], v[70:73]
	v_mfma_f32_16x16x32_bf16 v[74:77], v[154:157], v[216:219], v[74:77]
	v_mfma_f32_16x16x32_bf16 v[74:77], v[158:161], v[220:223], v[74:77]
	v_mfma_f32_16x16x32_bf16 v[78:81], v[150:153], v[220:223], v[78:81]
	v_mfma_f32_16x16x32_bf16 v[78:81], v[146:149], v[216:219], v[78:81]
	s_setprio 0
	s_barrier
	s_add_u32 s98, s84, 0x80
	s_addc_u32 s99, s85, 0
	s_add_u32 s100, vcc_lo, 0x80
	s_addc_u32 s101, vcc_hi, 0
	s_add_i32 s0, s0, s20
	s_mov_b32 m0, s0
	ds_read_b128 v[182:185], v177 offset:49152
	ds_read_b128 v[186:189], v177 offset:50176
	ds_read_b128 v[190:193], v177 offset:51200
	ds_read_b128 v[204:207], v177 offset:52224
	ds_read_b128 v[208:211], v177 offset:53248
	ds_read_b128 v[212:215], v177 offset:54272
	ds_read_b128 v[216:219], v177 offset:55296
	ds_read_b128 v[220:223], v177 offset:56320
	global_load_lds_dwordx4 v132, s[98:99]
	s_add_i32 m0, s0, 0x2000
	s_add_u32 s84, s84, 0x80080
	s_addc_u32 s85, s85, 0
	s_add_i32 s0, s1, s20
	global_load_lds_dwordx4 v130, s[98:99]
	s_mov_b32 m0, s0
	s_nop 0
	global_load_lds_dwordx4 v132, s[84:85]
	s_add_i32 m0, s0, 0x2000
	s_nop 0
	global_load_lds_dwordx4 v130, s[84:85]
	s_mov_b32 m0, s40
	s_nop 0
	global_load_lds_dwordx4 v132, s[100:101]
	s_mov_b32 m0, s41
	s_nop 0
	global_load_lds_dwordx4 v130, s[100:101]
	s_waitcnt vmcnt(8)
	s_waitcnt lgkmcnt(0)
	s_barrier
	s_setprio 1
	s_waitcnt lgkmcnt(0)
	v_mfma_f32_16x16x32_bf16 v[62:65], v[146:149], v[182:185], v[62:65]
	v_mfma_f32_16x16x32_bf16 v[62:65], v[150:153], v[186:189], v[62:65]
	v_mfma_f32_16x16x32_bf16 v[58:61], v[158:161], v[186:189], v[58:61]
	v_mfma_f32_16x16x32_bf16 v[58:61], v[154:157], v[182:185], v[58:61]
	v_mfma_f32_16x16x32_bf16 v[54:57], v[162:165], v[182:185], v[54:57]
	v_mfma_f32_16x16x32_bf16 v[54:57], v[166:169], v[186:189], v[54:57]
	v_mfma_f32_16x16x32_bf16 v[50:53], v[178:181], v[186:189], v[50:53]
	v_mfma_f32_16x16x32_bf16 v[50:53], v[170:173], v[182:185], v[50:53]
	v_mfma_f32_16x16x32_bf16 v[34:37], v[170:173], v[190:193], v[34:37]
	v_mfma_f32_16x16x32_bf16 v[34:37], v[178:181], v[204:207], v[34:37]
	v_mfma_f32_16x16x32_bf16 v[38:41], v[166:169], v[204:207], v[38:41]
	v_mfma_f32_16x16x32_bf16 v[38:41], v[162:165], v[190:193], v[38:41]
	v_mfma_f32_16x16x32_bf16 v[42:45], v[154:157], v[190:193], v[42:45]
	v_mfma_f32_16x16x32_bf16 v[42:45], v[158:161], v[204:207], v[42:45]
	v_mfma_f32_16x16x32_bf16 v[46:49], v[150:153], v[204:207], v[46:49]
	v_mfma_f32_16x16x32_bf16 v[46:49], v[146:149], v[190:193], v[46:49]
	v_mfma_f32_16x16x32_bf16 v[30:33], v[146:149], v[208:211], v[30:33]
	v_mfma_f32_16x16x32_bf16 v[30:33], v[150:153], v[212:215], v[30:33]
	v_mfma_f32_16x16x32_bf16 v[26:29], v[158:161], v[212:215], v[26:29]
	v_mfma_f32_16x16x32_bf16 v[26:29], v[154:157], v[208:211], v[26:29]
	v_mfma_f32_16x16x32_bf16 v[22:25], v[162:165], v[208:211], v[22:25]
	v_mfma_f32_16x16x32_bf16 v[22:25], v[166:169], v[212:215], v[22:25]
	v_mfma_f32_16x16x32_bf16 v[18:21], v[178:181], v[212:215], v[18:21]
	v_mfma_f32_16x16x32_bf16 v[18:21], v[170:173], v[208:211], v[18:21]
	v_mfma_f32_16x16x32_bf16 v[2:5], v[170:173], v[216:219], v[2:5]
	v_mfma_f32_16x16x32_bf16 v[2:5], v[178:181], v[220:223], v[2:5]
	v_mfma_f32_16x16x32_bf16 v[6:9], v[166:169], v[220:223], v[6:9]
	v_mfma_f32_16x16x32_bf16 v[6:9], v[162:165], v[216:219], v[6:9]
	v_mfma_f32_16x16x32_bf16 v[10:13], v[154:157], v[216:219], v[10:13]
	v_mfma_f32_16x16x32_bf16 v[10:13], v[158:161], v[220:223], v[10:13]
	v_mfma_f32_16x16x32_bf16 v[14:17], v[150:153], v[220:223], v[14:17]
	v_mfma_f32_16x16x32_bf16 v[14:17], v[146:149], v[216:219], v[14:17]
	s_setprio 0
	s_barrier
	s_add_i32 s65, s65, 2
	s_add_u32 s76, s76, 0x100
	s_addc_u32 s77, s77, 0
	s_add_u32 s51, s51, 0x100
	s_addc_u32 s58, s58, 0
	s_cmp_gt_u32 s65, 29
	s_cbranch_scc1 .LBB0_264
	s_branch .LBB0_262

.LBB0_284:
	s_ashr_i32 s49, s48, 31
	s_lshl_b64 s[22:23], s[48:49], 20
	s_add_u32 s50, s79, s22
	s_addc_u32 s51, s28, s23
	s_and_b64 s[22:23], s[4:5], exec
	s_cselect_b32 s21, s51, s77
	s_cselect_b32 s22, s50, s76
	s_ashr_i32 s39, s38, 31
	s_lshl_b64 s[62:63], s[38:39], 20
	s_add_u32 s62, s29, s62
	s_addc_u32 s63, s31, s63
	s_and_b64 s[64:65], s[4:5], exec
	s_cselect_b32 s23, s63, s71
	s_cselect_b32 s39, s62, s70
	s_ashr_i32 s7, s6, 31
	s_lshl_b32 s64, s40, 8
	s_lshl_b64 vcc, s[6:7], 10
	s_ashr_i32 s0, s6, 5
	s_ashr_i32 s65, s64, 31
	s_add_u32 s76, s76, 0x80080
	v_lshl_add_u64 v[2:3], s[64:65], 2, v[166:167]
	v_mov_b32_e32 v4, 0x5800
	s_addc_u32 s77, s77, 0
	v_lshl_add_u64 v[130:131], v[168:169], 0, vcc
	v_mad_i64_i32 v[132:133], vcc, s0, v4, v[2:3]
	s_add_u32 s7, s70, 0x100
	s_addc_u32 s41, s71, 0
	s_mov_b32 s43, -2
	s_branch .LBB0_286

.Lpeel_disp_ino:
	s_cmp_lg_u32 s43, -2
	s_cbranch_scc1 .LBB0_285
	s_add_u32 s0, s76, 0xfff80080
	s_addc_u32 s1, s77, -1
	s_and_b64 s[70:71], s[70:71], exec
	s_cselect_b32 vcc_hi, s21, s1
	s_cselect_b32 vcc_lo, s22, s0
	s_cselect_b32 s71, s23, s41
	s_cselect_b32 s70, s39, s7
	s_add_i32 s0, 0, 0x10000
	s_add_i32 s1, 0, 0x14000
	v_add_u32_e32 v146, s0, v1
	v_add_u32_e32 v174, s1, v1
	ds_read_b128 v[134:137], v146
	ds_read_b128 v[138:141], v146 offset:1024
	ds_read_b128 v[142:145], v146 offset:2048
	ds_read_b128 v[146:149], v146 offset:3072
	ds_read_b128 v[150:153], v174
	ds_read_b128 v[154:157], v174 offset:1024
	ds_read_b128 v[158:161], v174 offset:2048
	ds_read_b128 v[174:177], v174 offset:3072
	s_add_i32 m0, s67, 0xc000
	ds_read_b128 v[178:181], v222
	ds_read_b128 v[182:185], v222 offset:1024
	ds_read_b128 v[186:189], v222 offset:2048
	ds_read_b128 v[190:193], v222 offset:3072
	ds_read_b128 v[204:207], v222 offset:4096
	ds_read_b128 v[208:211], v222 offset:5120
	ds_read_b128 v[212:215], v222 offset:6144
	ds_read_b128 v[216:219], v222 offset:7168
	global_load_lds_dwordx4 v170, s[76:77]
	s_add_i32 m0, s67, 0xe000
	s_nop 0
	global_load_lds_dwordx4 v172, s[76:77]
	s_waitcnt vmcnt(8)
	s_waitcnt lgkmcnt(0)
	s_barrier
	s_setprio 1
	s_waitcnt lgkmcnt(0)
	v_mfma_f32_16x16x32_bf16 v[126:129], v[134:137], v[178:181], 0
	v_mfma_f32_16x16x32_bf16 v[126:129], v[138:141], v[182:185], v[126:129]
	v_mfma_f32_16x16x32_bf16 v[122:125], v[146:149], v[182:185], 0
	v_mfma_f32_16x16x32_bf16 v[122:125], v[142:145], v[178:181], v[122:125]
	v_mfma_f32_16x16x32_bf16 v[118:121], v[150:153], v[178:181], 0
	v_mfma_f32_16x16x32_bf16 v[118:121], v[154:157], v[182:185], v[118:121]
	v_mfma_f32_16x16x32_bf16 v[114:117], v[174:177], v[182:185], 0
	v_mfma_f32_16x16x32_bf16 v[114:117], v[158:161], v[178:181], v[114:117]
	v_mfma_f32_16x16x32_bf16 v[98:101], v[158:161], v[186:189], 0
	v_mfma_f32_16x16x32_bf16 v[98:101], v[174:177], v[190:193], v[98:101]
	v_mfma_f32_16x16x32_bf16 v[102:105], v[154:157], v[190:193], 0
	v_mfma_f32_16x16x32_bf16 v[102:105], v[150:153], v[186:189], v[102:105]
	v_mfma_f32_16x16x32_bf16 v[106:109], v[142:145], v[186:189], 0
	v_mfma_f32_16x16x32_bf16 v[106:109], v[146:149], v[190:193], v[106:109]
	v_mfma_f32_16x16x32_bf16 v[110:113], v[138:141], v[190:193], 0
	v_mfma_f32_16x16x32_bf16 v[110:113], v[134:137], v[186:189], v[110:113]
	v_mfma_f32_16x16x32_bf16 v[94:97], v[134:137], v[204:207], 0
	v_mfma_f32_16x16x32_bf16 v[94:97], v[138:141], v[208:211], v[94:97]
	v_mfma_f32_16x16x32_bf16 v[90:93], v[146:149], v[208:211], 0
	v_mfma_f32_16x16x32_bf16 v[90:93], v[142:145], v[204:207], v[90:93]
	v_mfma_f32_16x16x32_bf16 v[86:89], v[150:153], v[204:207], 0
	v_mfma_f32_16x16x32_bf16 v[86:89], v[154:157], v[208:211], v[86:89]
	v_mfma_f32_16x16x32_bf16 v[82:85], v[174:177], v[208:211], 0
	v_mfma_f32_16x16x32_bf16 v[82:85], v[158:161], v[204:207], v[82:85]
	v_mfma_f32_16x16x32_bf16 v[66:69], v[158:161], v[212:215], 0
	v_mfma_f32_16x16x32_bf16 v[66:69], v[174:177], v[216:219], v[66:69]
	v_mfma_f32_16x16x32_bf16 v[70:73], v[154:157], v[216:219], 0
	v_mfma_f32_16x16x32_bf16 v[70:73], v[150:153], v[212:215], v[70:73]
	v_mfma_f32_16x16x32_bf16 v[74:77], v[142:145], v[212:215], 0
	v_mfma_f32_16x16x32_bf16 v[74:77], v[146:149], v[216:219], v[74:77]
	v_mfma_f32_16x16x32_bf16 v[78:81], v[138:141], v[216:219], 0
	v_mfma_f32_16x16x32_bf16 v[78:81], v[134:137], v[212:215], v[78:81]
	s_setprio 0
	s_barrier
	s_add_i32 s0, s0, s54
	s_mov_b32 m0, s0
	ds_read_b128 v[178:181], v222 offset:16384
	ds_read_b128 v[182:185], v222 offset:17408
	ds_read_b128 v[186:189], v222 offset:18432
	ds_read_b128 v[190:193], v222 offset:19456
	ds_read_b128 v[204:207], v222 offset:20480
	ds_read_b128 v[208:211], v222 offset:21504
	ds_read_b128 v[212:215], v222 offset:22528
	ds_read_b128 v[216:219], v222 offset:23552
	global_load_lds_dwordx4 v164, s[70:71]
	s_add_i32 m0, s0, 0x2000
	s_add_u32 s44, s70, 0x80000
	s_addc_u32 s45, s71, 0
	s_add_i32 s0, s1, s54
	global_load_lds_dwordx4 v162, s[70:71]
	s_mov_b32 m0, s0
	s_nop 0
	global_load_lds_dwordx4 v164, s[44:45]
	s_add_i32 m0, s0, 0x2000
	s_nop 0
	global_load_lds_dwordx4 v162, s[44:45]
	s_mov_b32 m0, s67
	s_nop 0
	global_load_lds_dwordx4 v164, vcc
	s_mov_b32 m0, s68
	s_nop 0
	global_load_lds_dwordx4 v162, vcc
	s_waitcnt vmcnt(8)
	s_waitcnt lgkmcnt(0)
	s_barrier
	s_setprio 1
	s_waitcnt lgkmcnt(0)
	v_mfma_f32_16x16x32_bf16 v[62:65], v[134:137], v[178:181], 0
	v_mfma_f32_16x16x32_bf16 v[62:65], v[138:141], v[182:185], v[62:65]
	v_mfma_f32_16x16x32_bf16 v[58:61], v[146:149], v[182:185], 0
	v_mfma_f32_16x16x32_bf16 v[58:61], v[142:145], v[178:181], v[58:61]
	v_mfma_f32_16x16x32_bf16 v[54:57], v[150:153], v[178:181], 0
	v_mfma_f32_16x16x32_bf16 v[54:57], v[154:157], v[182:185], v[54:57]
	v_mfma_f32_16x16x32_bf16 v[50:53], v[174:177], v[182:185], 0
	v_mfma_f32_16x16x32_bf16 v[50:53], v[158:161], v[178:181], v[50:53]
	v_mfma_f32_16x16x32_bf16 v[34:37], v[158:161], v[186:189], 0
	v_mfma_f32_16x16x32_bf16 v[34:37], v[174:177], v[190:193], v[34:37]
	v_mfma_f32_16x16x32_bf16 v[38:41], v[154:157], v[190:193], 0
	v_mfma_f32_16x16x32_bf16 v[38:41], v[150:153], v[186:189], v[38:41]
	v_mfma_f32_16x16x32_bf16 v[42:45], v[142:145], v[186:189], 0
	v_mfma_f32_16x16x32_bf16 v[42:45], v[146:149], v[190:193], v[42:45]
	v_mfma_f32_16x16x32_bf16 v[46:49], v[138:141], v[190:193], 0
	v_mfma_f32_16x16x32_bf16 v[46:49], v[134:137], v[186:189], v[46:49]
	v_mfma_f32_16x16x32_bf16 v[30:33], v[134:137], v[204:207], 0
	v_mfma_f32_16x16x32_bf16 v[30:33], v[138:141], v[208:211], v[30:33]
	v_mfma_f32_16x16x32_bf16 v[26:29], v[146:149], v[208:211], 0
	v_mfma_f32_16x16x32_bf16 v[26:29], v[142:145], v[204:207], v[26:29]
	v_mfma_f32_16x16x32_bf16 v[22:25], v[150:153], v[204:207], 0
	v_mfma_f32_16x16x32_bf16 v[22:25], v[154:157], v[208:211], v[22:25]
	v_mfma_f32_16x16x32_bf16 v[18:21], v[174:177], v[208:211], 0
	v_mfma_f32_16x16x32_bf16 v[18:21], v[158:161], v[204:207], v[18:21]
	v_mfma_f32_16x16x32_bf16 v[2:5], v[158:161], v[212:215], 0
	v_mfma_f32_16x16x32_bf16 v[2:5], v[174:177], v[216:219], v[2:5]
	v_mfma_f32_16x16x32_bf16 v[6:9], v[154:157], v[216:219], 0
	v_mfma_f32_16x16x32_bf16 v[6:9], v[150:153], v[212:215], v[6:9]
	v_mfma_f32_16x16x32_bf16 v[10:13], v[142:145], v[212:215], 0
	v_mfma_f32_16x16x32_bf16 v[10:13], v[146:149], v[216:219], v[10:13]
	v_mfma_f32_16x16x32_bf16 v[14:17], v[138:141], v[216:219], 0
	v_mfma_f32_16x16x32_bf16 v[14:17], v[134:137], v[212:215], v[14:17]
	s_setprio 0
	s_barrier
	s_add_i32 s0, 0, 0x18000
	s_add_i32 s1, 0, 0x1c000
	v_add_u32_e32 v146, s0, v1
	v_add_u32_e32 v174, s1, v1
	ds_read_b128 v[134:137], v146
	ds_read_b128 v[138:141], v146 offset:1024
	ds_read_b128 v[142:145], v146 offset:2048
	ds_read_b128 v[146:149], v146 offset:3072
	ds_read_b128 v[150:153], v174
	ds_read_b128 v[154:157], v174 offset:1024
	ds_read_b128 v[158:161], v174 offset:2048
	ds_read_b128 v[174:177], v174 offset:3072
	s_add_u32 s44, vcc_lo, 0x80000
	s_addc_u32 s45, vcc_hi, 0
	s_mov_b32 m0, s8
	ds_read_b128 v[178:181], v222 offset:32768
	ds_read_b128 v[182:185], v222 offset:33792
	ds_read_b128 v[186:189], v222 offset:34816
	ds_read_b128 v[190:193], v222 offset:35840
	ds_read_b128 v[204:207], v222 offset:36864
	ds_read_b128 v[208:211], v222 offset:37888
	ds_read_b128 v[212:215], v222 offset:38912
	ds_read_b128 v[216:219], v222 offset:39936
	global_load_lds_dwordx4 v164, s[44:45]
	s_mov_b32 m0, s9
	s_nop 0
	global_load_lds_dwordx4 v162, s[44:45]
	s_waitcnt vmcnt(8)
	s_waitcnt lgkmcnt(0)
	s_barrier
	s_setprio 1
	s_waitcnt lgkmcnt(0)
	v_mfma_f32_16x16x32_bf16 v[126:129], v[134:137], v[178:181], v[126:129]
	v_mfma_f32_16x16x32_bf16 v[126:129], v[138:141], v[182:185], v[126:129]
	v_mfma_f32_16x16x32_bf16 v[122:125], v[146:149], v[182:185], v[122:125]
	v_mfma_f32_16x16x32_bf16 v[122:125], v[142:145], v[178:181], v[122:125]
	v_mfma_f32_16x16x32_bf16 v[118:121], v[150:153], v[178:181], v[118:121]
	v_mfma_f32_16x16x32_bf16 v[118:121], v[154:157], v[182:185], v[118:121]
	v_mfma_f32_16x16x32_bf16 v[114:117], v[174:177], v[182:185], v[114:117]
	v_mfma_f32_16x16x32_bf16 v[114:117], v[158:161], v[178:181], v[114:117]
	v_mfma_f32_16x16x32_bf16 v[98:101], v[158:161], v[186:189], v[98:101]
	v_mfma_f32_16x16x32_bf16 v[98:101], v[174:177], v[190:193], v[98:101]
	v_mfma_f32_16x16x32_bf16 v[102:105], v[154:157], v[190:193], v[102:105]
	v_mfma_f32_16x16x32_bf16 v[102:105], v[150:153], v[186:189], v[102:105]
	v_mfma_f32_16x16x32_bf16 v[106:109], v[142:145], v[186:189], v[106:109]
	v_mfma_f32_16x16x32_bf16 v[106:109], v[146:149], v[190:193], v[106:109]
	v_mfma_f32_16x16x32_bf16 v[110:113], v[138:141], v[190:193], v[110:113]
	v_mfma_f32_16x16x32_bf16 v[110:113], v[134:137], v[186:189], v[110:113]
	v_mfma_f32_16x16x32_bf16 v[94:97], v[134:137], v[204:207], v[94:97]
	v_mfma_f32_16x16x32_bf16 v[94:97], v[138:141], v[208:211], v[94:97]
	v_mfma_f32_16x16x32_bf16 v[90:93], v[146:149], v[208:211], v[90:93]
	v_mfma_f32_16x16x32_bf16 v[90:93], v[142:145], v[204:207], v[90:93]
	v_mfma_f32_16x16x32_bf16 v[86:89], v[150:153], v[204:207], v[86:89]
	v_mfma_f32_16x16x32_bf16 v[86:89], v[154:157], v[208:211], v[86:89]
	v_mfma_f32_16x16x32_bf16 v[82:85], v[174:177], v[208:211], v[82:85]
	v_mfma_f32_16x16x32_bf16 v[82:85], v[158:161], v[204:207], v[82:85]
	v_mfma_f32_16x16x32_bf16 v[66:69], v[158:161], v[212:215], v[66:69]
	v_mfma_f32_16x16x32_bf16 v[66:69], v[174:177], v[216:219], v[66:69]
	v_mfma_f32_16x16x32_bf16 v[70:73], v[154:157], v[216:219], v[70:73]
	v_mfma_f32_16x16x32_bf16 v[70:73], v[150:153], v[212:215], v[70:73]
	v_mfma_f32_16x16x32_bf16 v[74:77], v[142:145], v[212:215], v[74:77]
	v_mfma_f32_16x16x32_bf16 v[74:77], v[146:149], v[216:219], v[74:77]
	v_mfma_f32_16x16x32_bf16 v[78:81], v[138:141], v[216:219], v[78:81]
	v_mfma_f32_16x16x32_bf16 v[78:81], v[134:137], v[212:215], v[78:81]
	s_setprio 0
	s_barrier
	s_add_u32 s98, s70, 0x80
	s_addc_u32 s99, s71, 0
	s_add_u32 s100, vcc_lo, 0x80
	s_addc_u32 s101, vcc_hi, 0
	s_add_i32 s0, s0, s54
	s_mov_b32 m0, s0
	ds_read_b128 v[178:181], v222 offset:49152
	ds_read_b128 v[182:185], v222 offset:50176
	ds_read_b128 v[186:189], v222 offset:51200
	ds_read_b128 v[190:193], v222 offset:52224
	ds_read_b128 v[204:207], v222 offset:53248
	ds_read_b128 v[208:211], v222 offset:54272
	ds_read_b128 v[212:215], v222 offset:55296
	ds_read_b128 v[216:219], v222 offset:56320
	global_load_lds_dwordx4 v164, s[98:99]
	s_add_i32 m0, s0, 0x2000
	s_add_u32 s44, s70, 0x80080
	s_addc_u32 s45, s71, 0
	s_add_i32 s0, s1, s54
	global_load_lds_dwordx4 v162, s[98:99]
	s_mov_b32 m0, s0
	s_nop 0
	global_load_lds_dwordx4 v164, s[44:45]
	s_add_i32 m0, s0, 0x2000
	s_nop 0
	global_load_lds_dwordx4 v162, s[44:45]
	s_mov_b32 m0, s27
	s_nop 0
	global_load_lds_dwordx4 v164, s[100:101]
	s_mov_b32 m0, s26
	s_nop 0
	global_load_lds_dwordx4 v162, s[100:101]
	s_waitcnt vmcnt(8)
	s_waitcnt lgkmcnt(0)
	s_barrier
	s_setprio 1
	s_waitcnt lgkmcnt(0)
	v_mfma_f32_16x16x32_bf16 v[62:65], v[134:137], v[178:181], v[62:65]
	v_mfma_f32_16x16x32_bf16 v[62:65], v[138:141], v[182:185], v[62:65]
	v_mfma_f32_16x16x32_bf16 v[58:61], v[146:149], v[182:185], v[58:61]
	v_mfma_f32_16x16x32_bf16 v[58:61], v[142:145], v[178:181], v[58:61]
	v_mfma_f32_16x16x32_bf16 v[54:57], v[150:153], v[178:181], v[54:57]
	v_mfma_f32_16x16x32_bf16 v[54:57], v[154:157], v[182:185], v[54:57]
	v_mfma_f32_16x16x32_bf16 v[50:53], v[174:177], v[182:185], v[50:53]
	v_mfma_f32_16x16x32_bf16 v[50:53], v[158:161], v[178:181], v[50:53]
	v_mfma_f32_16x16x32_bf16 v[34:37], v[158:161], v[186:189], v[34:37]
	v_mfma_f32_16x16x32_bf16 v[34:37], v[174:177], v[190:193], v[34:37]
	v_mfma_f32_16x16x32_bf16 v[38:41], v[154:157], v[190:193], v[38:41]
	v_mfma_f32_16x16x32_bf16 v[38:41], v[150:153], v[186:189], v[38:41]
	v_mfma_f32_16x16x32_bf16 v[42:45], v[142:145], v[186:189], v[42:45]
	v_mfma_f32_16x16x32_bf16 v[42:45], v[146:149], v[190:193], v[42:45]
	v_mfma_f32_16x16x32_bf16 v[46:49], v[138:141], v[190:193], v[46:49]
	v_mfma_f32_16x16x32_bf16 v[46:49], v[134:137], v[186:189], v[46:49]
	v_mfma_f32_16x16x32_bf16 v[30:33], v[134:137], v[204:207], v[30:33]
	v_mfma_f32_16x16x32_bf16 v[30:33], v[138:141], v[208:211], v[30:33]
	v_mfma_f32_16x16x32_bf16 v[26:29], v[146:149], v[208:211], v[26:29]
	v_mfma_f32_16x16x32_bf16 v[26:29], v[142:145], v[204:207], v[26:29]
	v_mfma_f32_16x16x32_bf16 v[22:25], v[150:153], v[204:207], v[22:25]
	v_mfma_f32_16x16x32_bf16 v[22:25], v[154:157], v[208:211], v[22:25]
	v_mfma_f32_16x16x32_bf16 v[18:21], v[174:177], v[208:211], v[18:21]
	v_mfma_f32_16x16x32_bf16 v[18:21], v[158:161], v[204:207], v[18:21]
	v_mfma_f32_16x16x32_bf16 v[2:5], v[158:161], v[212:215], v[2:5]
	v_mfma_f32_16x16x32_bf16 v[2:5], v[174:177], v[216:219], v[2:5]
	v_mfma_f32_16x16x32_bf16 v[6:9], v[154:157], v[216:219], v[6:9]
	v_mfma_f32_16x16x32_bf16 v[6:9], v[150:153], v[212:215], v[6:9]
	v_mfma_f32_16x16x32_bf16 v[10:13], v[142:145], v[212:215], v[10:13]
	v_mfma_f32_16x16x32_bf16 v[10:13], v[146:149], v[216:219], v[10:13]
	v_mfma_f32_16x16x32_bf16 v[14:17], v[138:141], v[216:219], v[14:17]
	v_mfma_f32_16x16x32_bf16 v[14:17], v[134:137], v[212:215], v[14:17]
	s_setprio 0
	s_barrier
	s_add_i32 s43, s43, 2
	s_add_u32 s76, s76, 0x100
	s_addc_u32 s77, s77, 0
	s_add_u32 s7, s7, 0x100
	s_addc_u32 s41, s41, 0
	s_cmp_gt_u32 s43, 29
	s_cbranch_scc1 .LBB0_288
	s_branch .LBB0_286

.LBB0_508:
	s_ashr_i32 s53, s52, 31
	s_lshl_b64 s[0:1], s[52:53], 20
	s_add_u32 s62, s20, s0
	s_addc_u32 s63, s21, s1
	s_and_b64 s[0:1], s[6:7], exec
	s_cselect_b32 s22, s63, s77
	s_cselect_b32 s23, s62, s76
	s_ashr_i32 s51, s50, 31
	s_lshl_b64 s[0:1], s[50:51], 20
	s_add_u32 s84, s26, s0
	s_addc_u32 s85, s27, s1
	s_and_b64 s[0:1], s[6:7], exec
	s_cselect_b32 s41, s85, s91
	s_cselect_b32 s44, s84, s90
	s_lshl_b32 s64, s57, 8
	s_ashr_i32 s65, s64, 31
	s_lshl_b64 s[0:1], s[64:65], 2
	s_ashr_i32 s18, s40, 5
	v_lshl_add_u64 v[2:3], v[206:207], 0, s[0:1]
	v_lshl_add_u64 v[4:5], v[208:209], 0, s[0:1]
	v_mad_i64_i32 v[70:71], s[0:1], s18, v235, v[2:3]
	s_add_u32 s51, s90, 0x100
	v_mad_i64_i32 v[72:73], s[0:1], s18, v235, v[4:5]
	s_addc_u32 s53, s91, 0
	s_mov_b32 s57, -2
	s_branch .LBB0_510

.Lpeel_disp_out:
	s_cmp_lg_u32 s57, -2
	s_cbranch_scc1 .LBB0_509
	s_add_u32 s90, s76, 0x100
	s_addc_u32 s91, s77, 0
	s_and_b64 s[0:1], s[70:71], exec
	s_cselect_b32 vcc_hi, s22, s91
	s_cselect_b32 vcc_lo, s23, s90
	s_cselect_b32 s71, s41, s53
	s_cselect_b32 s70, s44, s51
	s_add_i32 s0, 0, 0x10000
	s_add_i32 s18, 0, 0x14000
	v_add_u32_e32 v114, s0, v1
	v_add_u32_e32 v154, s18, v1
	ds_read_b128 v[78:81], v114
	ds_read_b128 v[90:93], v114 offset:1024
	ds_read_b128 v[102:105], v114 offset:2048
	ds_read_b128 v[114:117], v114 offset:3072
	ds_read_b128 v[126:129], v154
	ds_read_b128 v[134:137], v154 offset:1024
	ds_read_b128 v[142:145], v154 offset:2048
	ds_read_b128 v[154:157], v154 offset:3072
	s_add_i32 m0, s29, 0xc000
	ds_read_b128 v[158:161], v237
	ds_read_b128 v[162:165], v237 offset:1024
	ds_read_b128 v[166:169], v237 offset:2048
	ds_read_b128 v[178:181], v237 offset:3072
	ds_read_b128 v[182:185], v237 offset:4096
	ds_read_b128 v[186:189], v237 offset:5120
	ds_read_b128 v[190:193], v237 offset:6144
	ds_read_b128 v[214:217], v237 offset:7168
	global_load_lds_dwordx4 v210, s[76:77]
	s_add_i32 m0, s29, 0xe000
	s_nop 0
	global_load_lds_dwordx4 v212, s[76:77]
	s_waitcnt vmcnt(8)
	s_waitcnt lgkmcnt(0)
	s_barrier
	s_setprio 1
	s_waitcnt lgkmcnt(0)
	v_mfma_f32_16x16x32_bf16 v[174:177], v[78:81], v[158:161], 0
	v_mfma_f32_16x16x32_bf16 v[174:177], v[90:93], v[162:165], v[174:177]
	v_mfma_f32_16x16x32_bf16 v[170:173], v[114:117], v[162:165], 0
	v_mfma_f32_16x16x32_bf16 v[170:173], v[102:105], v[158:161], v[170:173]
	v_mfma_f32_16x16x32_bf16 v[150:153], v[126:129], v[158:161], 0
	v_mfma_f32_16x16x32_bf16 v[150:153], v[134:137], v[162:165], v[150:153]
	v_mfma_f32_16x16x32_bf16 v[146:149], v[154:157], v[162:165], 0
	v_mfma_f32_16x16x32_bf16 v[146:149], v[142:145], v[158:161], v[146:149]
	v_mfma_f32_16x16x32_bf16 v[118:121], v[142:145], v[166:169], 0
	v_mfma_f32_16x16x32_bf16 v[118:121], v[154:157], v[178:181], v[118:121]
	v_mfma_f32_16x16x32_bf16 v[122:125], v[134:137], v[178:181], 0
	v_mfma_f32_16x16x32_bf16 v[122:125], v[126:129], v[166:169], v[122:125]
	v_mfma_f32_16x16x32_bf16 v[130:133], v[102:105], v[166:169], 0
	v_mfma_f32_16x16x32_bf16 v[130:133], v[114:117], v[178:181], v[130:133]
	v_mfma_f32_16x16x32_bf16 v[138:141], v[90:93], v[178:181], 0
	v_mfma_f32_16x16x32_bf16 v[138:141], v[78:81], v[166:169], v[138:141]
	v_mfma_f32_16x16x32_bf16 v[110:113], v[78:81], v[182:185], 0
	v_mfma_f32_16x16x32_bf16 v[110:113], v[90:93], v[186:189], v[110:113]
	v_mfma_f32_16x16x32_bf16 v[106:109], v[114:117], v[186:189], 0
	v_mfma_f32_16x16x32_bf16 v[106:109], v[102:105], v[182:185], v[106:109]
	v_mfma_f32_16x16x32_bf16 v[98:101], v[126:129], v[182:185], 0
	v_mfma_f32_16x16x32_bf16 v[98:101], v[134:137], v[186:189], v[98:101]
	v_mfma_f32_16x16x32_bf16 v[94:97], v[154:157], v[186:189], 0
	v_mfma_f32_16x16x32_bf16 v[94:97], v[142:145], v[182:185], v[94:97]
	v_mfma_f32_16x16x32_bf16 v[66:69], v[142:145], v[190:193], 0
	v_mfma_f32_16x16x32_bf16 v[66:69], v[154:157], v[214:217], v[66:69]
	v_mfma_f32_16x16x32_bf16 v[74:77], v[134:137], v[214:217], 0
	v_mfma_f32_16x16x32_bf16 v[74:77], v[126:129], v[190:193], v[74:77]
	v_mfma_f32_16x16x32_bf16 v[82:85], v[102:105], v[190:193], 0
	v_mfma_f32_16x16x32_bf16 v[82:85], v[114:117], v[214:217], v[82:85]
	v_mfma_f32_16x16x32_bf16 v[86:89], v[90:93], v[214:217], 0
	v_mfma_f32_16x16x32_bf16 v[86:89], v[78:81], v[190:193], v[86:89]
	s_setprio 0
	s_barrier
	s_add_i32 s0, s0, s28
	s_mov_b32 m0, s0
	ds_read_b128 v[158:161], v237 offset:16384
	ds_read_b128 v[162:165], v237 offset:17408
	ds_read_b128 v[166:169], v237 offset:18432
	ds_read_b128 v[178:181], v237 offset:19456
	ds_read_b128 v[182:185], v237 offset:20480
	ds_read_b128 v[186:189], v237 offset:21504
	ds_read_b128 v[190:193], v237 offset:22528
	ds_read_b128 v[214:217], v237 offset:23552
	global_load_lds_dwordx4 v194, s[70:71]
	s_add_i32 m0, s0, 0x2000
	s_add_u32 s0, s70, 0x80000
	s_addc_u32 s1, s71, 0
	s_add_i32 s18, s18, s28
	global_load_lds_dwordx4 v204, s[70:71]
	s_mov_b32 m0, s18
	s_nop 0
	global_load_lds_dwordx4 v194, s[0:1]
	s_add_i32 m0, s18, 0x2000
	s_nop 0
	global_load_lds_dwordx4 v204, s[0:1]
	s_mov_b32 m0, s29
	s_nop 0
	global_load_lds_dwordx4 v194, vcc
	s_mov_b32 m0, s31
	s_nop 0
	global_load_lds_dwordx4 v204, vcc
	s_waitcnt vmcnt(8)
	s_waitcnt lgkmcnt(0)
	s_barrier
	s_setprio 1
	s_waitcnt lgkmcnt(0)
	v_mfma_f32_16x16x32_bf16 v[62:65], v[78:81], v[158:161], 0
	v_mfma_f32_16x16x32_bf16 v[62:65], v[90:93], v[162:165], v[62:65]
	v_mfma_f32_16x16x32_bf16 v[58:61], v[114:117], v[162:165], 0
	v_mfma_f32_16x16x32_bf16 v[58:61], v[102:105], v[158:161], v[58:61]
	v_mfma_f32_16x16x32_bf16 v[54:57], v[126:129], v[158:161], 0
	v_mfma_f32_16x16x32_bf16 v[54:57], v[134:137], v[162:165], v[54:57]
	v_mfma_f32_16x16x32_bf16 v[50:53], v[154:157], v[162:165], 0
	v_mfma_f32_16x16x32_bf16 v[50:53], v[142:145], v[158:161], v[50:53]
	v_mfma_f32_16x16x32_bf16 v[34:37], v[142:145], v[166:169], 0
	v_mfma_f32_16x16x32_bf16 v[34:37], v[154:157], v[178:181], v[34:37]
	v_mfma_f32_16x16x32_bf16 v[38:41], v[134:137], v[178:181], 0
	v_mfma_f32_16x16x32_bf16 v[38:41], v[126:129], v[166:169], v[38:41]
	v_mfma_f32_16x16x32_bf16 v[42:45], v[102:105], v[166:169], 0
	v_mfma_f32_16x16x32_bf16 v[42:45], v[114:117], v[178:181], v[42:45]
	v_mfma_f32_16x16x32_bf16 v[46:49], v[90:93], v[178:181], 0
	v_mfma_f32_16x16x32_bf16 v[46:49], v[78:81], v[166:169], v[46:49]
	v_mfma_f32_16x16x32_bf16 v[30:33], v[78:81], v[182:185], 0
	v_mfma_f32_16x16x32_bf16 v[30:33], v[90:93], v[186:189], v[30:33]
	v_mfma_f32_16x16x32_bf16 v[26:29], v[114:117], v[186:189], 0
	v_mfma_f32_16x16x32_bf16 v[26:29], v[102:105], v[182:185], v[26:29]
	v_mfma_f32_16x16x32_bf16 v[22:25], v[126:129], v[182:185], 0
	v_mfma_f32_16x16x32_bf16 v[22:25], v[134:137], v[186:189], v[22:25]
	v_mfma_f32_16x16x32_bf16 v[18:21], v[154:157], v[186:189], 0
	v_mfma_f32_16x16x32_bf16 v[18:21], v[142:145], v[182:185], v[18:21]
	v_mfma_f32_16x16x32_bf16 v[2:5], v[142:145], v[190:193], 0
	v_mfma_f32_16x16x32_bf16 v[2:5], v[154:157], v[214:217], v[2:5]
	v_mfma_f32_16x16x32_bf16 v[6:9], v[134:137], v[214:217], 0
	v_mfma_f32_16x16x32_bf16 v[6:9], v[126:129], v[190:193], v[6:9]
	v_mfma_f32_16x16x32_bf16 v[10:13], v[102:105], v[190:193], 0
	v_mfma_f32_16x16x32_bf16 v[10:13], v[114:117], v[214:217], v[10:13]
	v_mfma_f32_16x16x32_bf16 v[14:17], v[90:93], v[214:217], 0
	v_mfma_f32_16x16x32_bf16 v[14:17], v[78:81], v[190:193], v[14:17]
	s_setprio 0
	s_barrier
	s_add_i32 s18, 0, 0x18000
	s_add_i32 s19, 0, 0x1c000
	v_add_u32_e32 v114, s18, v1
	v_add_u32_e32 v154, s19, v1
	ds_read_b128 v[78:81], v114
	ds_read_b128 v[90:93], v114 offset:1024
	ds_read_b128 v[102:105], v114 offset:2048
	ds_read_b128 v[114:117], v114 offset:3072
	ds_read_b128 v[126:129], v154
	ds_read_b128 v[134:137], v154 offset:1024
	ds_read_b128 v[142:145], v154 offset:2048
	ds_read_b128 v[154:157], v154 offset:3072
	s_add_u32 s0, vcc_lo, 0x80000
	s_addc_u32 s1, vcc_hi, 0
	s_mov_b32 m0, s33
	ds_read_b128 v[158:161], v237 offset:32768
	ds_read_b128 v[162:165], v237 offset:33792
	ds_read_b128 v[166:169], v237 offset:34816
	ds_read_b128 v[178:181], v237 offset:35840
	ds_read_b128 v[182:185], v237 offset:36864
	ds_read_b128 v[186:189], v237 offset:37888
	ds_read_b128 v[190:193], v237 offset:38912
	ds_read_b128 v[214:217], v237 offset:39936
	global_load_lds_dwordx4 v194, s[0:1]
	s_mov_b32 m0, s43
	s_nop 0
	global_load_lds_dwordx4 v204, s[0:1]
	s_waitcnt vmcnt(8)
	s_waitcnt lgkmcnt(0)
	s_barrier
	s_setprio 1
	s_waitcnt lgkmcnt(0)
	v_mfma_f32_16x16x32_bf16 v[174:177], v[78:81], v[158:161], v[174:177]
	v_mfma_f32_16x16x32_bf16 v[174:177], v[90:93], v[162:165], v[174:177]
	v_mfma_f32_16x16x32_bf16 v[170:173], v[114:117], v[162:165], v[170:173]
	v_mfma_f32_16x16x32_bf16 v[170:173], v[102:105], v[158:161], v[170:173]
	v_mfma_f32_16x16x32_bf16 v[150:153], v[126:129], v[158:161], v[150:153]
	v_mfma_f32_16x16x32_bf16 v[150:153], v[134:137], v[162:165], v[150:153]
	v_mfma_f32_16x16x32_bf16 v[146:149], v[154:157], v[162:165], v[146:149]
	v_mfma_f32_16x16x32_bf16 v[146:149], v[142:145], v[158:161], v[146:149]
	v_mfma_f32_16x16x32_bf16 v[118:121], v[142:145], v[166:169], v[118:121]
	v_mfma_f32_16x16x32_bf16 v[118:121], v[154:157], v[178:181], v[118:121]
	v_mfma_f32_16x16x32_bf16 v[122:125], v[134:137], v[178:181], v[122:125]
	v_mfma_f32_16x16x32_bf16 v[122:125], v[126:129], v[166:169], v[122:125]
	v_mfma_f32_16x16x32_bf16 v[130:133], v[102:105], v[166:169], v[130:133]
	v_mfma_f32_16x16x32_bf16 v[130:133], v[114:117], v[178:181], v[130:133]
	v_mfma_f32_16x16x32_bf16 v[138:141], v[90:93], v[178:181], v[138:141]
	v_mfma_f32_16x16x32_bf16 v[138:141], v[78:81], v[166:169], v[138:141]
	v_mfma_f32_16x16x32_bf16 v[110:113], v[78:81], v[182:185], v[110:113]
	v_mfma_f32_16x16x32_bf16 v[110:113], v[90:93], v[186:189], v[110:113]
	v_mfma_f32_16x16x32_bf16 v[106:109], v[114:117], v[186:189], v[106:109]
	v_mfma_f32_16x16x32_bf16 v[106:109], v[102:105], v[182:185], v[106:109]
	v_mfma_f32_16x16x32_bf16 v[98:101], v[126:129], v[182:185], v[98:101]
	v_mfma_f32_16x16x32_bf16 v[98:101], v[134:137], v[186:189], v[98:101]
	v_mfma_f32_16x16x32_bf16 v[94:97], v[154:157], v[186:189], v[94:97]
	v_mfma_f32_16x16x32_bf16 v[94:97], v[142:145], v[182:185], v[94:97]
	v_mfma_f32_16x16x32_bf16 v[66:69], v[142:145], v[190:193], v[66:69]
	v_mfma_f32_16x16x32_bf16 v[66:69], v[154:157], v[214:217], v[66:69]
	v_mfma_f32_16x16x32_bf16 v[74:77], v[134:137], v[214:217], v[74:77]
	v_mfma_f32_16x16x32_bf16 v[74:77], v[126:129], v[190:193], v[74:77]
	v_mfma_f32_16x16x32_bf16 v[82:85], v[102:105], v[190:193], v[82:85]
	v_mfma_f32_16x16x32_bf16 v[82:85], v[114:117], v[214:217], v[82:85]
	v_mfma_f32_16x16x32_bf16 v[86:89], v[90:93], v[214:217], v[86:89]
	v_mfma_f32_16x16x32_bf16 v[86:89], v[78:81], v[190:193], v[86:89]
	s_setprio 0
	s_barrier
	s_add_u32 s98, s70, 0x80
	s_addc_u32 s99, s71, 0
	s_add_u32 s100, vcc_lo, 0x80
	s_addc_u32 s101, vcc_hi, 0
	s_add_i32 s0, s18, s28
	s_mov_b32 m0, s0
	ds_read_b128 v[158:161], v237 offset:49152
	ds_read_b128 v[162:165], v237 offset:50176
	ds_read_b128 v[166:169], v237 offset:51200
	ds_read_b128 v[178:181], v237 offset:52224
	ds_read_b128 v[182:185], v237 offset:53248
	ds_read_b128 v[186:189], v237 offset:54272
	ds_read_b128 v[190:193], v237 offset:55296
	ds_read_b128 v[214:217], v237 offset:56320
	global_load_lds_dwordx4 v194, s[98:99]
	s_add_i32 m0, s0, 0x2000
	s_add_u32 s0, s70, 0x80080
	s_addc_u32 s1, s71, 0
	s_add_i32 s18, s19, s28
	global_load_lds_dwordx4 v204, s[98:99]
	s_mov_b32 m0, s18
	s_nop 0
	global_load_lds_dwordx4 v194, s[0:1]
	s_add_i32 m0, s18, 0x2000
	s_nop 0
	global_load_lds_dwordx4 v204, s[0:1]
	s_mov_b32 m0, s68
	s_nop 0
	global_load_lds_dwordx4 v194, s[100:101]
	s_mov_b32 m0, s79
	s_nop 0
	global_load_lds_dwordx4 v204, s[100:101]
	s_waitcnt vmcnt(8)
	s_waitcnt lgkmcnt(0)
	s_barrier
	s_setprio 1
	s_waitcnt lgkmcnt(0)
	v_mfma_f32_16x16x32_bf16 v[62:65], v[78:81], v[158:161], v[62:65]
	v_mfma_f32_16x16x32_bf16 v[62:65], v[90:93], v[162:165], v[62:65]
	v_mfma_f32_16x16x32_bf16 v[58:61], v[114:117], v[162:165], v[58:61]
	v_mfma_f32_16x16x32_bf16 v[58:61], v[102:105], v[158:161], v[58:61]
	v_mfma_f32_16x16x32_bf16 v[54:57], v[126:129], v[158:161], v[54:57]
	v_mfma_f32_16x16x32_bf16 v[54:57], v[134:137], v[162:165], v[54:57]
	v_mfma_f32_16x16x32_bf16 v[50:53], v[154:157], v[162:165], v[50:53]
	v_mfma_f32_16x16x32_bf16 v[50:53], v[142:145], v[158:161], v[50:53]
	v_mfma_f32_16x16x32_bf16 v[34:37], v[142:145], v[166:169], v[34:37]
	v_mfma_f32_16x16x32_bf16 v[34:37], v[154:157], v[178:181], v[34:37]
	v_mfma_f32_16x16x32_bf16 v[38:41], v[134:137], v[178:181], v[38:41]
	v_mfma_f32_16x16x32_bf16 v[38:41], v[126:129], v[166:169], v[38:41]
	v_mfma_f32_16x16x32_bf16 v[42:45], v[102:105], v[166:169], v[42:45]
	v_mfma_f32_16x16x32_bf16 v[42:45], v[114:117], v[178:181], v[42:45]
	v_mfma_f32_16x16x32_bf16 v[46:49], v[90:93], v[178:181], v[46:49]
	v_mfma_f32_16x16x32_bf16 v[46:49], v[78:81], v[166:169], v[46:49]
	v_mfma_f32_16x16x32_bf16 v[30:33], v[78:81], v[182:185], v[30:33]
	v_mfma_f32_16x16x32_bf16 v[30:33], v[90:93], v[186:189], v[30:33]
	v_mfma_f32_16x16x32_bf16 v[26:29], v[114:117], v[186:189], v[26:29]
	v_mfma_f32_16x16x32_bf16 v[26:29], v[102:105], v[182:185], v[26:29]
	v_mfma_f32_16x16x32_bf16 v[22:25], v[126:129], v[182:185], v[22:25]
	v_mfma_f32_16x16x32_bf16 v[22:25], v[134:137], v[186:189], v[22:25]
	v_mfma_f32_16x16x32_bf16 v[18:21], v[154:157], v[186:189], v[18:21]
	v_mfma_f32_16x16x32_bf16 v[18:21], v[142:145], v[182:185], v[18:21]
	v_mfma_f32_16x16x32_bf16 v[2:5], v[142:145], v[190:193], v[2:5]
	v_mfma_f32_16x16x32_bf16 v[2:5], v[154:157], v[214:217], v[2:5]
	v_mfma_f32_16x16x32_bf16 v[6:9], v[134:137], v[214:217], v[6:9]
	v_mfma_f32_16x16x32_bf16 v[6:9], v[126:129], v[190:193], v[6:9]
	v_mfma_f32_16x16x32_bf16 v[10:13], v[102:105], v[190:193], v[10:13]
	v_mfma_f32_16x16x32_bf16 v[10:13], v[114:117], v[214:217], v[10:13]
	v_mfma_f32_16x16x32_bf16 v[14:17], v[90:93], v[214:217], v[14:17]
	v_mfma_f32_16x16x32_bf16 v[14:17], v[78:81], v[190:193], v[14:17]
	s_setprio 0
	s_barrier
	s_add_i32 s57, s57, 2
	s_add_u32 s51, s51, 0x100
	s_addc_u32 s53, s53, 0
	s_cmp_gt_u32 s57, 29
	s_mov_b64 s[76:77], s[90:91]
	s_cbranch_scc1 .LBB0_512
	s_branch .LBB0_510

.LBB0_580:
	s_ashr_i32 s47, s46, 31
	s_lshl_b64 s[0:1], s[46:47], 20
	s_add_u32 s48, s20, s0
	s_addc_u32 s49, s21, s1
	s_and_b64 s[0:1], s[6:7], exec
	s_cselect_b32 s22, s49, s63
	s_cselect_b32 s23, s48, s62
	s_ashr_i32 s39, s38, 31
	s_lshl_b64 s[0:1], s[38:39], 20
	s_add_u32 s50, s26, s0
	s_addc_u32 s51, s27, s1
	s_and_b64 s[0:1], s[6:7], exec
	s_cselect_b32 s39, s51, s65
	s_cselect_b32 s47, s50, s64
	s_ashr_i32 s53, s52, 31
	s_lshl_b32 s18, s44, 8
	s_lshl_b64 s[0:1], s[52:53], 10
	s_ashr_i32 s24, s52, 5
	s_ashr_i32 s19, s18, 31
	s_add_u32 s62, s62, 0x80080
	v_lshl_add_u64 v[2:3], s[18:19], 2, v[132:133]
	s_addc_u32 s63, s63, 0
	v_lshl_add_u64 v[140:141], v[134:135], 0, s[0:1]
	v_mad_i64_i32 v[142:143], s[0:1], s24, v236, v[2:3]
	s_add_u32 s53, s64, 0x100
	s_addc_u32 s58, s65, 0
	s_mov_b32 s76, -2
	s_branch .LBB0_582

.Lpeel_disp_gu:
	s_cmp_lg_u32 s76, -2
	s_cbranch_scc1 .LBB0_581
	s_add_u32 s18, s62, 0xfff80080
	s_addc_u32 s19, s63, -1
	s_and_b64 s[0:1], s[64:65], exec
	s_cselect_b32 s71, s22, s19
	s_cselect_b32 s70, s23, s18
	s_cselect_b32 s65, s39, s58
	s_cselect_b32 s64, s47, s53
	s_add_i32 s0, 0, 0x10000
	v_add_u32_e32 v153, s0, v1
	s_add_i32 s18, 0, 0x14000
	ds_read_b128 v[144:147], v153
	ds_read_b128 v[148:151], v153 offset:1024
	ds_read_b128 v[154:157], v153 offset:2048
	ds_read_b128 v[158:161], v153 offset:3072
	v_add_u32_e32 v153, s18, v1
	ds_read_b128 v[162:165], v153
	ds_read_b128 v[166:169], v153 offset:1024
	ds_read_b128 v[170:173], v153 offset:2048
	ds_read_b128 v[174:177], v153 offset:3072
	s_add_i32 m0, s29, 0xc000
	ds_read_b128 v[178:181], v152
	ds_read_b128 v[182:185], v152 offset:1024
	ds_read_b128 v[186:189], v152 offset:2048
	ds_read_b128 v[190:193], v152 offset:3072
	ds_read_b128 v[204:207], v152 offset:4096
	ds_read_b128 v[208:211], v152 offset:5120
	ds_read_b128 v[212:215], v152 offset:6144
	ds_read_b128 v[216:219], v152 offset:7168
	global_load_lds_dwordx4 v136, s[62:63]
	s_add_i32 m0, s29, 0xe000
	s_nop 0
	global_load_lds_dwordx4 v138, s[62:63]
	s_waitcnt vmcnt(8)
	s_waitcnt lgkmcnt(0)
	s_barrier
	s_setprio 1
	s_waitcnt lgkmcnt(0)
	v_mfma_f32_16x16x32_bf16 v[126:129], v[144:147], v[178:181], 0
	v_mfma_f32_16x16x32_bf16 v[126:129], v[148:151], v[182:185], v[126:129]
	v_mfma_f32_16x16x32_bf16 v[122:125], v[158:161], v[182:185], 0
	v_mfma_f32_16x16x32_bf16 v[122:125], v[154:157], v[178:181], v[122:125]
	v_mfma_f32_16x16x32_bf16 v[118:121], v[162:165], v[178:181], 0
	v_mfma_f32_16x16x32_bf16 v[118:121], v[166:169], v[182:185], v[118:121]
	v_mfma_f32_16x16x32_bf16 v[114:117], v[174:177], v[182:185], 0
	v_mfma_f32_16x16x32_bf16 v[114:117], v[170:173], v[178:181], v[114:117]
	v_mfma_f32_16x16x32_bf16 v[98:101], v[170:173], v[186:189], 0
	v_mfma_f32_16x16x32_bf16 v[98:101], v[174:177], v[190:193], v[98:101]
	v_mfma_f32_16x16x32_bf16 v[102:105], v[166:169], v[190:193], 0
	v_mfma_f32_16x16x32_bf16 v[102:105], v[162:165], v[186:189], v[102:105]
	v_mfma_f32_16x16x32_bf16 v[106:109], v[154:157], v[186:189], 0
	v_mfma_f32_16x16x32_bf16 v[106:109], v[158:161], v[190:193], v[106:109]
	v_mfma_f32_16x16x32_bf16 v[110:113], v[148:151], v[190:193], 0
	v_mfma_f32_16x16x32_bf16 v[110:113], v[144:147], v[186:189], v[110:113]
	v_mfma_f32_16x16x32_bf16 v[94:97], v[144:147], v[204:207], 0
	v_mfma_f32_16x16x32_bf16 v[94:97], v[148:151], v[208:211], v[94:97]
	v_mfma_f32_16x16x32_bf16 v[90:93], v[158:161], v[208:211], 0
	v_mfma_f32_16x16x32_bf16 v[90:93], v[154:157], v[204:207], v[90:93]
	v_mfma_f32_16x16x32_bf16 v[86:89], v[162:165], v[204:207], 0
	v_mfma_f32_16x16x32_bf16 v[86:89], v[166:169], v[208:211], v[86:89]
	v_mfma_f32_16x16x32_bf16 v[82:85], v[174:177], v[208:211], 0
	v_mfma_f32_16x16x32_bf16 v[82:85], v[170:173], v[204:207], v[82:85]
	v_mfma_f32_16x16x32_bf16 v[66:69], v[170:173], v[212:215], 0
	v_mfma_f32_16x16x32_bf16 v[66:69], v[174:177], v[216:219], v[66:69]
	v_mfma_f32_16x16x32_bf16 v[70:73], v[166:169], v[216:219], 0
	v_mfma_f32_16x16x32_bf16 v[70:73], v[162:165], v[212:215], v[70:73]
	v_mfma_f32_16x16x32_bf16 v[74:77], v[154:157], v[212:215], 0
	v_mfma_f32_16x16x32_bf16 v[74:77], v[158:161], v[216:219], v[74:77]
	v_mfma_f32_16x16x32_bf16 v[78:81], v[148:151], v[216:219], 0
	v_mfma_f32_16x16x32_bf16 v[78:81], v[144:147], v[212:215], v[78:81]
	s_setprio 0
	s_barrier
	s_add_i32 s0, s0, s28
	s_mov_b32 m0, s0
	ds_read_b128 v[178:181], v152 offset:16384
	ds_read_b128 v[182:185], v152 offset:17408
	ds_read_b128 v[186:189], v152 offset:18432
	ds_read_b128 v[190:193], v152 offset:19456
	ds_read_b128 v[204:207], v152 offset:20480
	ds_read_b128 v[208:211], v152 offset:21504
	ds_read_b128 v[212:215], v152 offset:22528
	ds_read_b128 v[216:219], v152 offset:23552
	global_load_lds_dwordx4 v194, s[64:65]
	s_add_i32 m0, s0, 0x2000
	s_add_u32 s0, s64, 0x80000
	s_addc_u32 s1, s65, 0
	s_add_i32 s18, s18, s28
	global_load_lds_dwordx4 v130, s[64:65]
	s_mov_b32 m0, s18
	s_nop 0
	global_load_lds_dwordx4 v194, s[0:1]
	s_add_i32 m0, s18, 0x2000
	s_nop 0
	global_load_lds_dwordx4 v130, s[0:1]
	s_mov_b32 m0, s29
	s_nop 0
	global_load_lds_dwordx4 v194, s[70:71]
	s_mov_b32 m0, s31
	s_nop 0
	global_load_lds_dwordx4 v130, s[70:71]
	s_waitcnt vmcnt(8)
	s_waitcnt lgkmcnt(0)
	s_barrier
	s_setprio 1
	s_waitcnt lgkmcnt(0)
	v_mfma_f32_16x16x32_bf16 v[62:65], v[144:147], v[178:181], 0
	v_mfma_f32_16x16x32_bf16 v[62:65], v[148:151], v[182:185], v[62:65]
	v_mfma_f32_16x16x32_bf16 v[58:61], v[158:161], v[182:185], 0
	v_mfma_f32_16x16x32_bf16 v[58:61], v[154:157], v[178:181], v[58:61]
	v_mfma_f32_16x16x32_bf16 v[54:57], v[162:165], v[178:181], 0
	v_mfma_f32_16x16x32_bf16 v[54:57], v[166:169], v[182:185], v[54:57]
	v_mfma_f32_16x16x32_bf16 v[50:53], v[174:177], v[182:185], 0
	v_mfma_f32_16x16x32_bf16 v[50:53], v[170:173], v[178:181], v[50:53]
	v_mfma_f32_16x16x32_bf16 v[34:37], v[170:173], v[186:189], 0
	v_mfma_f32_16x16x32_bf16 v[34:37], v[174:177], v[190:193], v[34:37]
	v_mfma_f32_16x16x32_bf16 v[38:41], v[166:169], v[190:193], 0
	v_mfma_f32_16x16x32_bf16 v[38:41], v[162:165], v[186:189], v[38:41]
	v_mfma_f32_16x16x32_bf16 v[42:45], v[154:157], v[186:189], 0
	v_mfma_f32_16x16x32_bf16 v[42:45], v[158:161], v[190:193], v[42:45]
	v_mfma_f32_16x16x32_bf16 v[46:49], v[148:151], v[190:193], 0
	v_mfma_f32_16x16x32_bf16 v[46:49], v[144:147], v[186:189], v[46:49]
	v_mfma_f32_16x16x32_bf16 v[30:33], v[144:147], v[204:207], 0
	v_mfma_f32_16x16x32_bf16 v[30:33], v[148:151], v[208:211], v[30:33]
	v_mfma_f32_16x16x32_bf16 v[26:29], v[158:161], v[208:211], 0
	v_mfma_f32_16x16x32_bf16 v[26:29], v[154:157], v[204:207], v[26:29]
	v_mfma_f32_16x16x32_bf16 v[22:25], v[162:165], v[204:207], 0
	v_mfma_f32_16x16x32_bf16 v[22:25], v[166:169], v[208:211], v[22:25]
	v_mfma_f32_16x16x32_bf16 v[18:21], v[174:177], v[208:211], 0
	v_mfma_f32_16x16x32_bf16 v[18:21], v[170:173], v[204:207], v[18:21]
	v_mfma_f32_16x16x32_bf16 v[2:5], v[170:173], v[212:215], 0
	v_mfma_f32_16x16x32_bf16 v[2:5], v[174:177], v[216:219], v[2:5]
	v_mfma_f32_16x16x32_bf16 v[6:9], v[166:169], v[216:219], 0
	v_mfma_f32_16x16x32_bf16 v[6:9], v[162:165], v[212:215], v[6:9]
	v_mfma_f32_16x16x32_bf16 v[10:13], v[154:157], v[212:215], 0
	v_mfma_f32_16x16x32_bf16 v[10:13], v[158:161], v[216:219], v[10:13]
	v_mfma_f32_16x16x32_bf16 v[14:17], v[148:151], v[216:219], 0
	v_mfma_f32_16x16x32_bf16 v[14:17], v[144:147], v[212:215], v[14:17]
	s_setprio 0
	s_barrier
	s_add_i32 s18, 0, 0x18000
	v_add_u32_e32 v153, s18, v1
	s_add_i32 s19, 0, 0x1c000
	ds_read_b128 v[144:147], v153
	ds_read_b128 v[148:151], v153 offset:1024
	ds_read_b128 v[154:157], v153 offset:2048
	ds_read_b128 v[158:161], v153 offset:3072
	v_add_u32_e32 v153, s19, v1
	ds_read_b128 v[162:165], v153
	ds_read_b128 v[166:169], v153 offset:1024
	ds_read_b128 v[170:173], v153 offset:2048
	ds_read_b128 v[174:177], v153 offset:3072
	s_add_u32 s0, s70, 0x80000
	s_addc_u32 s1, s71, 0
	s_mov_b32 m0, s33
	ds_read_b128 v[178:181], v152 offset:32768
	ds_read_b128 v[182:185], v152 offset:33792
	ds_read_b128 v[186:189], v152 offset:34816
	ds_read_b128 v[190:193], v152 offset:35840
	ds_read_b128 v[204:207], v152 offset:36864
	ds_read_b128 v[208:211], v152 offset:37888
	ds_read_b128 v[212:215], v152 offset:38912
	ds_read_b128 v[216:219], v152 offset:39936
	global_load_lds_dwordx4 v194, s[0:1]
	s_mov_b32 m0, s40
	s_nop 0
	global_load_lds_dwordx4 v130, s[0:1]
	s_waitcnt vmcnt(8)
	s_waitcnt lgkmcnt(0)
	s_barrier
	s_setprio 1
	s_waitcnt lgkmcnt(0)
	v_mfma_f32_16x16x32_bf16 v[126:129], v[144:147], v[178:181], v[126:129]
	v_mfma_f32_16x16x32_bf16 v[126:129], v[148:151], v[182:185], v[126:129]
	v_mfma_f32_16x16x32_bf16 v[122:125], v[158:161], v[182:185], v[122:125]
	v_mfma_f32_16x16x32_bf16 v[122:125], v[154:157], v[178:181], v[122:125]
	v_mfma_f32_16x16x32_bf16 v[118:121], v[162:165], v[178:181], v[118:121]
	v_mfma_f32_16x16x32_bf16 v[118:121], v[166:169], v[182:185], v[118:121]
	v_mfma_f32_16x16x32_bf16 v[114:117], v[174:177], v[182:185], v[114:117]
	v_mfma_f32_16x16x32_bf16 v[114:117], v[170:173], v[178:181], v[114:117]
	v_mfma_f32_16x16x32_bf16 v[98:101], v[170:173], v[186:189], v[98:101]
	v_mfma_f32_16x16x32_bf16 v[98:101], v[174:177], v[190:193], v[98:101]
	v_mfma_f32_16x16x32_bf16 v[102:105], v[166:169], v[190:193], v[102:105]
	v_mfma_f32_16x16x32_bf16 v[102:105], v[162:165], v[186:189], v[102:105]
	v_mfma_f32_16x16x32_bf16 v[106:109], v[154:157], v[186:189], v[106:109]
	v_mfma_f32_16x16x32_bf16 v[106:109], v[158:161], v[190:193], v[106:109]
	v_mfma_f32_16x16x32_bf16 v[110:113], v[148:151], v[190:193], v[110:113]
	v_mfma_f32_16x16x32_bf16 v[110:113], v[144:147], v[186:189], v[110:113]
	v_mfma_f32_16x16x32_bf16 v[94:97], v[144:147], v[204:207], v[94:97]
	v_mfma_f32_16x16x32_bf16 v[94:97], v[148:151], v[208:211], v[94:97]
	v_mfma_f32_16x16x32_bf16 v[90:93], v[158:161], v[208:211], v[90:93]
	v_mfma_f32_16x16x32_bf16 v[90:93], v[154:157], v[204:207], v[90:93]
	v_mfma_f32_16x16x32_bf16 v[86:89], v[162:165], v[204:207], v[86:89]
	v_mfma_f32_16x16x32_bf16 v[86:89], v[166:169], v[208:211], v[86:89]
	v_mfma_f32_16x16x32_bf16 v[82:85], v[174:177], v[208:211], v[82:85]
	v_mfma_f32_16x16x32_bf16 v[82:85], v[170:173], v[204:207], v[82:85]
	v_mfma_f32_16x16x32_bf16 v[66:69], v[170:173], v[212:215], v[66:69]
	v_mfma_f32_16x16x32_bf16 v[66:69], v[174:177], v[216:219], v[66:69]
	v_mfma_f32_16x16x32_bf16 v[70:73], v[166:169], v[216:219], v[70:73]
	v_mfma_f32_16x16x32_bf16 v[70:73], v[162:165], v[212:215], v[70:73]
	v_mfma_f32_16x16x32_bf16 v[74:77], v[154:157], v[212:215], v[74:77]
	v_mfma_f32_16x16x32_bf16 v[74:77], v[158:161], v[216:219], v[74:77]
	v_mfma_f32_16x16x32_bf16 v[78:81], v[148:151], v[216:219], v[78:81]
	v_mfma_f32_16x16x32_bf16 v[78:81], v[144:147], v[212:215], v[78:81]
	s_setprio 0
	s_barrier
	s_add_u32 s98, s64, 0x80
	s_addc_u32 s99, s65, 0
	s_add_u32 s100, s70, 0x80
	s_addc_u32 s101, s71, 0
	s_add_i32 s0, s18, s28
	s_mov_b32 m0, s0
	ds_read_b128 v[178:181], v152 offset:49152
	ds_read_b128 v[182:185], v152 offset:50176
	ds_read_b128 v[186:189], v152 offset:51200
	ds_read_b128 v[190:193], v152 offset:52224
	ds_read_b128 v[204:207], v152 offset:53248
	ds_read_b128 v[208:211], v152 offset:54272
	ds_read_b128 v[212:215], v152 offset:55296
	ds_read_b128 v[216:219], v152 offset:56320
	global_load_lds_dwordx4 v194, s[98:99]
	s_add_i32 m0, s0, 0x2000
	s_add_u32 s0, s64, 0x80080
	s_addc_u32 s1, s65, 0
	s_add_i32 s18, s19, s28
	global_load_lds_dwordx4 v130, s[98:99]
	s_mov_b32 m0, s18
	s_nop 0
	global_load_lds_dwordx4 v194, s[0:1]
	s_add_i32 m0, s18, 0x2000
	s_nop 0
	global_load_lds_dwordx4 v130, s[0:1]
	s_mov_b32 m0, s54
	s_nop 0
	global_load_lds_dwordx4 v194, s[100:101]
	s_mov_b32 m0, s57
	s_nop 0
	global_load_lds_dwordx4 v130, s[100:101]
	s_waitcnt vmcnt(8)
	s_waitcnt lgkmcnt(0)
	s_barrier
	s_setprio 1
	s_waitcnt lgkmcnt(0)
	v_mfma_f32_16x16x32_bf16 v[62:65], v[144:147], v[178:181], v[62:65]
	v_mfma_f32_16x16x32_bf16 v[62:65], v[148:151], v[182:185], v[62:65]
	v_mfma_f32_16x16x32_bf16 v[58:61], v[158:161], v[182:185], v[58:61]
	v_mfma_f32_16x16x32_bf16 v[58:61], v[154:157], v[178:181], v[58:61]
	v_mfma_f32_16x16x32_bf16 v[54:57], v[162:165], v[178:181], v[54:57]
	v_mfma_f32_16x16x32_bf16 v[54:57], v[166:169], v[182:185], v[54:57]
	v_mfma_f32_16x16x32_bf16 v[50:53], v[174:177], v[182:185], v[50:53]
	v_mfma_f32_16x16x32_bf16 v[50:53], v[170:173], v[178:181], v[50:53]
	v_mfma_f32_16x16x32_bf16 v[34:37], v[170:173], v[186:189], v[34:37]
	v_mfma_f32_16x16x32_bf16 v[34:37], v[174:177], v[190:193], v[34:37]
	v_mfma_f32_16x16x32_bf16 v[38:41], v[166:169], v[190:193], v[38:41]
	v_mfma_f32_16x16x32_bf16 v[38:41], v[162:165], v[186:189], v[38:41]
	v_mfma_f32_16x16x32_bf16 v[42:45], v[154:157], v[186:189], v[42:45]
	v_mfma_f32_16x16x32_bf16 v[42:45], v[158:161], v[190:193], v[42:45]
	v_mfma_f32_16x16x32_bf16 v[46:49], v[148:151], v[190:193], v[46:49]
	v_mfma_f32_16x16x32_bf16 v[46:49], v[144:147], v[186:189], v[46:49]
	v_mfma_f32_16x16x32_bf16 v[30:33], v[144:147], v[204:207], v[30:33]
	v_mfma_f32_16x16x32_bf16 v[30:33], v[148:151], v[208:211], v[30:33]
	v_mfma_f32_16x16x32_bf16 v[26:29], v[158:161], v[208:211], v[26:29]
	v_mfma_f32_16x16x32_bf16 v[26:29], v[154:157], v[204:207], v[26:29]
	v_mfma_f32_16x16x32_bf16 v[22:25], v[162:165], v[204:207], v[22:25]
	v_mfma_f32_16x16x32_bf16 v[22:25], v[166:169], v[208:211], v[22:25]
	v_mfma_f32_16x16x32_bf16 v[18:21], v[174:177], v[208:211], v[18:21]
	v_mfma_f32_16x16x32_bf16 v[18:21], v[170:173], v[204:207], v[18:21]
	v_mfma_f32_16x16x32_bf16 v[2:5], v[170:173], v[212:215], v[2:5]
	v_mfma_f32_16x16x32_bf16 v[2:5], v[174:177], v[216:219], v[2:5]
	v_mfma_f32_16x16x32_bf16 v[6:9], v[166:169], v[216:219], v[6:9]
	v_mfma_f32_16x16x32_bf16 v[6:9], v[162:165], v[212:215], v[6:9]
	v_mfma_f32_16x16x32_bf16 v[10:13], v[154:157], v[212:215], v[10:13]
	v_mfma_f32_16x16x32_bf16 v[10:13], v[158:161], v[216:219], v[10:13]
	v_mfma_f32_16x16x32_bf16 v[14:17], v[148:151], v[216:219], v[14:17]
	v_mfma_f32_16x16x32_bf16 v[14:17], v[144:147], v[212:215], v[14:17]
	s_setprio 0
	s_barrier
	s_add_i32 s76, s76, 2
	s_add_u32 s62, s62, 0x100
	s_addc_u32 s63, s63, 0
	s_add_u32 s53, s53, 0x100
	s_addc_u32 s58, s58, 0
	s_cmp_gt_u32 s76, 29
	s_cbranch_scc1 .LBB0_584
	s_branch .LBB0_582

.LBB0_644:
	s_lshl_b32 s6, s23, 8
	s_ashr_i32 s7, s6, 31
	s_lshl_b64 s[0:1], s[6:7], 2
	s_ashr_i32 s24, s22, 5
	v_lshl_add_u64 v[2:3], v[204:205], 0, s[0:1]
	v_mad_i64_i32 v[66:67], s[18:19], s24, v235, v[2:3]
	s_mul_hi_i32 s7, s24, 0xc000
	s_mul_i32 s24, s24, 0xc000
	s_add_u32 s18, s90, s24
	s_addc_u32 s7, s80, s7
	s_add_u32 s0, s18, s0
	s_addc_u32 s1, s7, s1
	s_add_u32 s7, s64, 0x100
	v_lshl_add_u64 v[68:69], s[0:1], 0, v[194:195]
	s_addc_u32 s23, s65, 0
	s_mov_b32 s41, -2
	s_branch .LBB0_646

.Lpeel_disp_down:
	s_cmp_lg_u32 s41, -2
	s_cbranch_scc1 .LBB0_645
	s_add_u32 s64, s8, 0x100
	s_addc_u32 s65, s9, 0
	s_and_b64 s[0:1], s[70:71], exec
	s_cselect_b32 s77, s63, s65
	s_cselect_b32 s76, s62, s64
	s_cselect_b32 s71, s85, s23
	s_cselect_b32 s70, s84, s7
	s_add_i32 s0, 0, 0x10000
	s_add_i32 s18, 0, 0x14000
	v_add_u32_e32 v106, s0, v1
	v_add_u32_e32 v154, s18, v1
	ds_read_b128 v[70:73], v106
	ds_read_b128 v[82:85], v106 offset:1024
	ds_read_b128 v[94:97], v106 offset:2048
	ds_read_b128 v[106:109], v106 offset:3072
	ds_read_b128 v[118:121], v154
	ds_read_b128 v[130:133], v154 offset:1024
	ds_read_b128 v[142:145], v154 offset:2048
	ds_read_b128 v[154:157], v154 offset:3072
	s_add_i32 m0, s29, 0xc000
	ds_read_b128 v[158:161], v237
	ds_read_b128 v[170:173], v237 offset:1024
	ds_read_b128 v[174:177], v237 offset:2048
	ds_read_b128 v[178:181], v237 offset:3072
	ds_read_b128 v[182:185], v237 offset:4096
	ds_read_b128 v[186:189], v237 offset:5120
	ds_read_b128 v[210:213], v237 offset:6144
	ds_read_b128 v[214:217], v237 offset:7168
	global_load_lds_dwordx4 v206, s[8:9]
	s_add_i32 m0, s29, 0xe000
	s_nop 0
	global_load_lds_dwordx4 v208, s[8:9]
	s_waitcnt vmcnt(8)
	s_waitcnt lgkmcnt(0)
	s_barrier
	s_setprio 1
	s_waitcnt lgkmcnt(0)
	v_mfma_f32_16x16x32_bf16 v[166:169], v[70:73], v[158:161], 0
	v_mfma_f32_16x16x32_bf16 v[166:169], v[82:85], v[170:173], v[166:169]
	v_mfma_f32_16x16x32_bf16 v[162:165], v[106:109], v[170:173], 0
	v_mfma_f32_16x16x32_bf16 v[162:165], v[94:97], v[158:161], v[162:165]
	v_mfma_f32_16x16x32_bf16 v[150:153], v[118:121], v[158:161], 0
	v_mfma_f32_16x16x32_bf16 v[150:153], v[130:133], v[170:173], v[150:153]
	v_mfma_f32_16x16x32_bf16 v[146:149], v[154:157], v[170:173], 0
	v_mfma_f32_16x16x32_bf16 v[146:149], v[142:145], v[158:161], v[146:149]
	v_mfma_f32_16x16x32_bf16 v[122:125], v[142:145], v[174:177], 0
	v_mfma_f32_16x16x32_bf16 v[122:125], v[154:157], v[178:181], v[122:125]
	v_mfma_f32_16x16x32_bf16 v[126:129], v[130:133], v[178:181], 0
	v_mfma_f32_16x16x32_bf16 v[126:129], v[118:121], v[174:177], v[126:129]
	v_mfma_f32_16x16x32_bf16 v[134:137], v[94:97], v[174:177], 0
	v_mfma_f32_16x16x32_bf16 v[134:137], v[106:109], v[178:181], v[134:137]
	v_mfma_f32_16x16x32_bf16 v[138:141], v[82:85], v[178:181], 0
	v_mfma_f32_16x16x32_bf16 v[138:141], v[70:73], v[174:177], v[138:141]
	v_mfma_f32_16x16x32_bf16 v[114:117], v[70:73], v[182:185], 0
	v_mfma_f32_16x16x32_bf16 v[114:117], v[82:85], v[186:189], v[114:117]
	v_mfma_f32_16x16x32_bf16 v[110:113], v[106:109], v[186:189], 0
	v_mfma_f32_16x16x32_bf16 v[110:113], v[94:97], v[182:185], v[110:113]
	v_mfma_f32_16x16x32_bf16 v[102:105], v[118:121], v[182:185], 0
	v_mfma_f32_16x16x32_bf16 v[102:105], v[130:133], v[186:189], v[102:105]
	v_mfma_f32_16x16x32_bf16 v[98:101], v[154:157], v[186:189], 0
	v_mfma_f32_16x16x32_bf16 v[98:101], v[142:145], v[182:185], v[98:101]
	v_mfma_f32_16x16x32_bf16 v[74:77], v[142:145], v[210:213], 0
	v_mfma_f32_16x16x32_bf16 v[74:77], v[154:157], v[214:217], v[74:77]
	v_mfma_f32_16x16x32_bf16 v[78:81], v[130:133], v[214:217], 0
	v_mfma_f32_16x16x32_bf16 v[78:81], v[118:121], v[210:213], v[78:81]
	v_mfma_f32_16x16x32_bf16 v[86:89], v[94:97], v[210:213], 0
	v_mfma_f32_16x16x32_bf16 v[86:89], v[106:109], v[214:217], v[86:89]
	v_mfma_f32_16x16x32_bf16 v[90:93], v[82:85], v[214:217], 0
	v_mfma_f32_16x16x32_bf16 v[90:93], v[70:73], v[210:213], v[90:93]
	s_setprio 0
	s_barrier
	s_add_i32 s0, s0, s28
	s_mov_b32 m0, s0
	ds_read_b128 v[158:161], v237 offset:16384
	ds_read_b128 v[170:173], v237 offset:17408
	ds_read_b128 v[174:177], v237 offset:18432
	ds_read_b128 v[178:181], v237 offset:19456
	ds_read_b128 v[182:185], v237 offset:20480
	ds_read_b128 v[186:189], v237 offset:21504
	ds_read_b128 v[210:213], v237 offset:22528
	ds_read_b128 v[214:217], v237 offset:23552
	global_load_lds_dwordx4 v192, s[70:71]
	s_add_i32 m0, s0, 0x2000
	s_add_u32 s0, s70, 0x160000
	s_addc_u32 s1, s71, 0
	s_add_i32 s8, s18, s28
	global_load_lds_dwordx4 v190, s[70:71]
	s_mov_b32 m0, s8
	s_nop 0
	global_load_lds_dwordx4 v192, s[0:1]
	s_add_i32 m0, s8, 0x2000
	s_nop 0
	global_load_lds_dwordx4 v190, s[0:1]
	s_mov_b32 m0, s29
	s_nop 0
	global_load_lds_dwordx4 v192, s[76:77]
	s_mov_b32 m0, s31
	s_nop 0
	global_load_lds_dwordx4 v190, s[76:77]
	s_waitcnt vmcnt(8)
	s_waitcnt lgkmcnt(0)
	s_barrier
	s_setprio 1
	s_waitcnt lgkmcnt(0)
	v_mfma_f32_16x16x32_bf16 v[62:65], v[70:73], v[158:161], 0
	v_mfma_f32_16x16x32_bf16 v[62:65], v[82:85], v[170:173], v[62:65]
	v_mfma_f32_16x16x32_bf16 v[58:61], v[106:109], v[170:173], 0
	v_mfma_f32_16x16x32_bf16 v[58:61], v[94:97], v[158:161], v[58:61]
	v_mfma_f32_16x16x32_bf16 v[54:57], v[118:121], v[158:161], 0
	v_mfma_f32_16x16x32_bf16 v[54:57], v[130:133], v[170:173], v[54:57]
	v_mfma_f32_16x16x32_bf16 v[50:53], v[154:157], v[170:173], 0
	v_mfma_f32_16x16x32_bf16 v[50:53], v[142:145], v[158:161], v[50:53]
	v_mfma_f32_16x16x32_bf16 v[34:37], v[142:145], v[174:177], 0
	v_mfma_f32_16x16x32_bf16 v[34:37], v[154:157], v[178:181], v[34:37]
	v_mfma_f32_16x16x32_bf16 v[38:41], v[130:133], v[178:181], 0
	v_mfma_f32_16x16x32_bf16 v[38:41], v[118:121], v[174:177], v[38:41]
	v_mfma_f32_16x16x32_bf16 v[42:45], v[94:97], v[174:177], 0
	v_mfma_f32_16x16x32_bf16 v[42:45], v[106:109], v[178:181], v[42:45]
	v_mfma_f32_16x16x32_bf16 v[46:49], v[82:85], v[178:181], 0
	v_mfma_f32_16x16x32_bf16 v[46:49], v[70:73], v[174:177], v[46:49]
	v_mfma_f32_16x16x32_bf16 v[30:33], v[70:73], v[182:185], 0
	v_mfma_f32_16x16x32_bf16 v[30:33], v[82:85], v[186:189], v[30:33]
	v_mfma_f32_16x16x32_bf16 v[26:29], v[106:109], v[186:189], 0
	v_mfma_f32_16x16x32_bf16 v[26:29], v[94:97], v[182:185], v[26:29]
	v_mfma_f32_16x16x32_bf16 v[22:25], v[118:121], v[182:185], 0
	v_mfma_f32_16x16x32_bf16 v[22:25], v[130:133], v[186:189], v[22:25]
	v_mfma_f32_16x16x32_bf16 v[18:21], v[154:157], v[186:189], 0
	v_mfma_f32_16x16x32_bf16 v[18:21], v[142:145], v[182:185], v[18:21]
	v_mfma_f32_16x16x32_bf16 v[2:5], v[142:145], v[210:213], 0
	v_mfma_f32_16x16x32_bf16 v[2:5], v[154:157], v[214:217], v[2:5]
	v_mfma_f32_16x16x32_bf16 v[6:9], v[130:133], v[214:217], 0
	v_mfma_f32_16x16x32_bf16 v[6:9], v[118:121], v[210:213], v[6:9]
	v_mfma_f32_16x16x32_bf16 v[10:13], v[94:97], v[210:213], 0
	v_mfma_f32_16x16x32_bf16 v[10:13], v[106:109], v[214:217], v[10:13]
	v_mfma_f32_16x16x32_bf16 v[14:17], v[82:85], v[214:217], 0
	v_mfma_f32_16x16x32_bf16 v[14:17], v[70:73], v[210:213], v[14:17]
	s_setprio 0
	s_barrier
	s_add_i32 s8, 0, 0x18000
	s_add_i32 s9, 0, 0x1c000
	v_add_u32_e32 v106, s8, v1
	v_add_u32_e32 v154, s9, v1
	ds_read_b128 v[70:73], v106
	ds_read_b128 v[82:85], v106 offset:1024
	ds_read_b128 v[94:97], v106 offset:2048
	ds_read_b128 v[106:109], v106 offset:3072
	ds_read_b128 v[118:121], v154
	ds_read_b128 v[130:133], v154 offset:1024
	ds_read_b128 v[142:145], v154 offset:2048
	ds_read_b128 v[154:157], v154 offset:3072
	s_add_u32 s0, s76, 0x160000
	s_addc_u32 s1, s77, 0
	s_mov_b32 m0, s33
	ds_read_b128 v[158:161], v237 offset:32768
	ds_read_b128 v[170:173], v237 offset:33792
	ds_read_b128 v[174:177], v237 offset:34816
	ds_read_b128 v[178:181], v237 offset:35840
	ds_read_b128 v[182:185], v237 offset:36864
	ds_read_b128 v[186:189], v237 offset:37888
	ds_read_b128 v[210:213], v237 offset:38912
	ds_read_b128 v[214:217], v237 offset:39936
	global_load_lds_dwordx4 v192, s[0:1]
	s_mov_b32 m0, s43
	s_nop 0
	global_load_lds_dwordx4 v190, s[0:1]
	s_waitcnt vmcnt(8)
	s_waitcnt lgkmcnt(0)
	s_barrier
	s_setprio 1
	s_waitcnt lgkmcnt(0)
	v_mfma_f32_16x16x32_bf16 v[166:169], v[70:73], v[158:161], v[166:169]
	v_mfma_f32_16x16x32_bf16 v[166:169], v[82:85], v[170:173], v[166:169]
	v_mfma_f32_16x16x32_bf16 v[162:165], v[106:109], v[170:173], v[162:165]
	v_mfma_f32_16x16x32_bf16 v[162:165], v[94:97], v[158:161], v[162:165]
	v_mfma_f32_16x16x32_bf16 v[150:153], v[118:121], v[158:161], v[150:153]
	v_mfma_f32_16x16x32_bf16 v[150:153], v[130:133], v[170:173], v[150:153]
	v_mfma_f32_16x16x32_bf16 v[146:149], v[154:157], v[170:173], v[146:149]
	v_mfma_f32_16x16x32_bf16 v[146:149], v[142:145], v[158:161], v[146:149]
	v_mfma_f32_16x16x32_bf16 v[122:125], v[142:145], v[174:177], v[122:125]
	v_mfma_f32_16x16x32_bf16 v[122:125], v[154:157], v[178:181], v[122:125]
	v_mfma_f32_16x16x32_bf16 v[126:129], v[130:133], v[178:181], v[126:129]
	v_mfma_f32_16x16x32_bf16 v[126:129], v[118:121], v[174:177], v[126:129]
	v_mfma_f32_16x16x32_bf16 v[134:137], v[94:97], v[174:177], v[134:137]
	v_mfma_f32_16x16x32_bf16 v[134:137], v[106:109], v[178:181], v[134:137]
	v_mfma_f32_16x16x32_bf16 v[138:141], v[82:85], v[178:181], v[138:141]
	v_mfma_f32_16x16x32_bf16 v[138:141], v[70:73], v[174:177], v[138:141]
	v_mfma_f32_16x16x32_bf16 v[114:117], v[70:73], v[182:185], v[114:117]
	v_mfma_f32_16x16x32_bf16 v[114:117], v[82:85], v[186:189], v[114:117]
	v_mfma_f32_16x16x32_bf16 v[110:113], v[106:109], v[186:189], v[110:113]
	v_mfma_f32_16x16x32_bf16 v[110:113], v[94:97], v[182:185], v[110:113]
	v_mfma_f32_16x16x32_bf16 v[102:105], v[118:121], v[182:185], v[102:105]
	v_mfma_f32_16x16x32_bf16 v[102:105], v[130:133], v[186:189], v[102:105]
	v_mfma_f32_16x16x32_bf16 v[98:101], v[154:157], v[186:189], v[98:101]
	v_mfma_f32_16x16x32_bf16 v[98:101], v[142:145], v[182:185], v[98:101]
	v_mfma_f32_16x16x32_bf16 v[74:77], v[142:145], v[210:213], v[74:77]
	v_mfma_f32_16x16x32_bf16 v[74:77], v[154:157], v[214:217], v[74:77]
	v_mfma_f32_16x16x32_bf16 v[78:81], v[130:133], v[214:217], v[78:81]
	v_mfma_f32_16x16x32_bf16 v[78:81], v[118:121], v[210:213], v[78:81]
	v_mfma_f32_16x16x32_bf16 v[86:89], v[94:97], v[210:213], v[86:89]
	v_mfma_f32_16x16x32_bf16 v[86:89], v[106:109], v[214:217], v[86:89]
	v_mfma_f32_16x16x32_bf16 v[90:93], v[82:85], v[214:217], v[90:93]
	v_mfma_f32_16x16x32_bf16 v[90:93], v[70:73], v[210:213], v[90:93]
	s_setprio 0
	s_barrier
	s_add_u32 s98, s70, 0x80
	s_addc_u32 s99, s71, 0
	s_add_u32 s100, s76, 0x80
	s_addc_u32 s101, s77, 0
	s_add_i32 s0, s8, s28
	s_mov_b32 m0, s0
	ds_read_b128 v[158:161], v237 offset:49152
	ds_read_b128 v[170:173], v237 offset:50176
	ds_read_b128 v[174:177], v237 offset:51200
	ds_read_b128 v[178:181], v237 offset:52224
	ds_read_b128 v[182:185], v237 offset:53248
	ds_read_b128 v[186:189], v237 offset:54272
	ds_read_b128 v[210:213], v237 offset:55296
	ds_read_b128 v[214:217], v237 offset:56320
	global_load_lds_dwordx4 v192, s[98:99]
	s_add_i32 m0, s0, 0x2000
	s_add_u32 s0, s70, 0x160080
	s_addc_u32 s1, s71, 0
	s_add_i32 s8, s9, s28
	global_load_lds_dwordx4 v190, s[98:99]
	s_mov_b32 m0, s8
	s_nop 0
	global_load_lds_dwordx4 v192, s[0:1]
	s_add_i32 m0, s8, 0x2000
	s_nop 0
	global_load_lds_dwordx4 v190, s[0:1]
	s_mov_b32 m0, s68
	s_nop 0
	global_load_lds_dwordx4 v192, s[100:101]
	s_mov_b32 m0, s79
	s_nop 0
	global_load_lds_dwordx4 v190, s[100:101]
	s_waitcnt vmcnt(8)
	s_waitcnt lgkmcnt(0)
	s_barrier
	s_setprio 1
	s_waitcnt lgkmcnt(0)
	v_mfma_f32_16x16x32_bf16 v[62:65], v[70:73], v[158:161], v[62:65]
	v_mfma_f32_16x16x32_bf16 v[62:65], v[82:85], v[170:173], v[62:65]
	v_mfma_f32_16x16x32_bf16 v[58:61], v[106:109], v[170:173], v[58:61]
	v_mfma_f32_16x16x32_bf16 v[58:61], v[94:97], v[158:161], v[58:61]
	v_mfma_f32_16x16x32_bf16 v[54:57], v[118:121], v[158:161], v[54:57]
	v_mfma_f32_16x16x32_bf16 v[54:57], v[130:133], v[170:173], v[54:57]
	v_mfma_f32_16x16x32_bf16 v[50:53], v[154:157], v[170:173], v[50:53]
	v_mfma_f32_16x16x32_bf16 v[50:53], v[142:145], v[158:161], v[50:53]
	v_mfma_f32_16x16x32_bf16 v[34:37], v[142:145], v[174:177], v[34:37]
	v_mfma_f32_16x16x32_bf16 v[34:37], v[154:157], v[178:181], v[34:37]
	v_mfma_f32_16x16x32_bf16 v[38:41], v[130:133], v[178:181], v[38:41]
	v_mfma_f32_16x16x32_bf16 v[38:41], v[118:121], v[174:177], v[38:41]
	v_mfma_f32_16x16x32_bf16 v[42:45], v[94:97], v[174:177], v[42:45]
	v_mfma_f32_16x16x32_bf16 v[42:45], v[106:109], v[178:181], v[42:45]
	v_mfma_f32_16x16x32_bf16 v[46:49], v[82:85], v[178:181], v[46:49]
	v_mfma_f32_16x16x32_bf16 v[46:49], v[70:73], v[174:177], v[46:49]
	v_mfma_f32_16x16x32_bf16 v[30:33], v[70:73], v[182:185], v[30:33]
	v_mfma_f32_16x16x32_bf16 v[30:33], v[82:85], v[186:189], v[30:33]
	v_mfma_f32_16x16x32_bf16 v[26:29], v[106:109], v[186:189], v[26:29]
	v_mfma_f32_16x16x32_bf16 v[26:29], v[94:97], v[182:185], v[26:29]
	v_mfma_f32_16x16x32_bf16 v[22:25], v[118:121], v[182:185], v[22:25]
	v_mfma_f32_16x16x32_bf16 v[22:25], v[130:133], v[186:189], v[22:25]
	v_mfma_f32_16x16x32_bf16 v[18:21], v[154:157], v[186:189], v[18:21]
	v_mfma_f32_16x16x32_bf16 v[18:21], v[142:145], v[182:185], v[18:21]
	v_mfma_f32_16x16x32_bf16 v[2:5], v[142:145], v[210:213], v[2:5]
	v_mfma_f32_16x16x32_bf16 v[2:5], v[154:157], v[214:217], v[2:5]
	v_mfma_f32_16x16x32_bf16 v[6:9], v[130:133], v[214:217], v[6:9]
	v_mfma_f32_16x16x32_bf16 v[6:9], v[118:121], v[210:213], v[6:9]
	v_mfma_f32_16x16x32_bf16 v[10:13], v[94:97], v[210:213], v[10:13]
	v_mfma_f32_16x16x32_bf16 v[10:13], v[106:109], v[214:217], v[10:13]
	v_mfma_f32_16x16x32_bf16 v[14:17], v[82:85], v[214:217], v[14:17]
	v_mfma_f32_16x16x32_bf16 v[14:17], v[70:73], v[210:213], v[14:17]
	s_setprio 0
	s_barrier
	s_add_i32 s41, s41, 2
	s_add_u32 s7, s7, 0x100
	s_addc_u32 s23, s23, 0
	s_cmpk_gt_u32 s41, 0x55
	s_mov_b64 s[8:9], s[64:65]
	s_cbranch_scc1 .LBB0_648
	s_branch .LBB0_646
